# first pair of each recurrence chunk waits lazily (counted lgkmcnt in consumption order) instead of draining all prologue LDS loads
# baseline (speedup 1.0000x reference)
.LBB0_824:
	s_add_i32 s39, s14, 1
	s_and_saveexec_b64 s[24:25], s[44:45]
	s_xor_b64 s[24:25], exec, s[24:25]
	s_cbranch_execz .LBB0_826
	s_and_b32 s26, s39, 1
	s_mul_i32 s27, s26, 0xc200
	s_add_i32 s27, s27, 0
	v_add_u32_e32 v0, s27, v41
	v_add_u32_e32 v43, s27, v51
	v_mov_b32_e32 v53, s27
	v_lshl_add_u32 v54, s26, 11, v39
	v_add_u32_e32 v55, 0x400, v54
	s_lshl_b32 s96, s39, 9
	s_add_u32 s96, s100, s96
	s_addc_u32 s97, s101, 0
	ds_read_b128 v[56:59], v0 offset:4096
	ds_read_b128 v[88:91], v0 offset:4608
	ds_read_b128 v[64:67], v0 offset:5632
	ds_read_b128 v[96:99], v0 offset:6144
	ds_read_b128 v[60:63], v0 offset:4352
	ds_read_b128 v[92:95], v0 offset:4864
	ds_read_b128 v[68:71], v0 offset:5888
	ds_read_b128 v[100:103], v0 offset:6400
	ds_read2st64_b32 v[104:105], v43 offset0:20 offset1:26
	v_mov_b32_e32 v108, s76
	s_waitcnt lgkmcnt(8)
	v_pk_mul_f32 v[124:125], v[2:3], v[56:57]
	s_load_dwordx8 s[28:35], s[96:97], 0x40
	s_waitcnt lgkmcnt(7)
	v_pk_mul_f32 v[126:127], v[2:3], v[88:89]
	ds_read_b128 v[72:75], v0 offset:7168
	s_waitcnt lgkmcnt(7)
	v_pk_mul_f32 v[128:129], v[2:3], v[64:65]
	ds_read_b128 v[76:79], v0 offset:7424
	s_waitcnt lgkmcnt(7)
	v_pk_mul_f32 v[134:135], v[2:3], v[96:97]
	ds_read_b128 v[80:83], v0 offset:8704
	v_pk_fma_f32 v[124:125], v[4:5], v[58:59], v[124:125]
	ds_read_b128 v[84:87], v0 offset:8960
	v_pk_fma_f32 v[126:127], v[4:5], v[90:91], v[126:127]
	ds_read2st64_b32 v[106:107], v43 offset0:32 offset1:38
	v_pk_fma_f32 v[128:129], v[4:5], v[66:67], v[128:129]
	v_pk_fma_f32 v[134:135], v[4:5], v[98:99], v[134:135]
	s_waitcnt lgkmcnt(9)
	v_pk_fma_f32 v[124:125], v[6:7], v[60:61], v[124:125]
	s_waitcnt lgkmcnt(8)
	v_pk_fma_f32 v[126:127], v[6:7], v[92:93], v[126:127]
	s_waitcnt lgkmcnt(7)
	v_pk_fma_f32 v[128:129], v[6:7], v[68:69], v[128:129]
	s_waitcnt lgkmcnt(6)
	v_pk_fma_f32 v[134:135], v[6:7], v[100:101], v[134:135]
	v_pk_fma_f32 v[124:125], v[8:9], v[62:63], v[124:125]
	v_pk_fma_f32 v[126:127], v[8:9], v[94:95], v[126:127]
	v_pk_fma_f32 v[128:129], v[8:9], v[70:71], v[128:129]
	v_pk_fma_f32 v[134:135], v[8:9], v[102:103], v[134:135]
	v_add_f32_e32 v124, v124, v125
	v_add_f32_e32 v126, v126, v127
	v_add_f32_e32 v128, v128, v129
	v_add_f32_e32 v134, v134, v135
	v_mul_f32_e32 v142, s80, v108
	v_add_f32_dpp v125, v124, v124 row_mirror row_mask:0xf bank_mask:0xf
	v_add_f32_dpp v125, v126, v126 row_mirror row_mask:0xf bank_mask:0xc
	v_add_f32_dpp v127, v128, v128 row_mirror row_mask:0xf bank_mask:0xf
	v_add_f32_dpp v127, v134, v134 row_mirror row_mask:0xf bank_mask:0xc
	v_add_f32_dpp v129, v125, v125 row_half_mirror row_mask:0xf bank_mask:0xf
	v_pk_mul_f32 v[2:3], v[2:3], v[142:143] op_sel_hi:[1,0]
	v_pk_mul_f32 v[4:5], v[4:5], v[142:143] op_sel_hi:[1,0]
	v_add_f32_dpp v129, v127, v127 row_half_mirror row_mask:0xf bank_mask:0xa
	v_pk_mul_f32 v[6:7], v[6:7], v[142:143] op_sel_hi:[1,0]
	v_pk_mul_f32 v[8:9], v[8:9], v[142:143] op_sel_hi:[1,0]
	v_add_f32_dpp v129, v129, v129 quad_perm:[1,0,3,2] row_mask:0xf bank_mask:0xf
	ds_read_b128 v[88:91], v0 offset:7680
	ds_read_b128 v[92:95], v0 offset:7936
	v_add_f32_dpp v129, v129, v129 quad_perm:[2,3,0,1] row_mask:0xf bank_mask:0xf
	ds_read_b128 v[96:99], v0 offset:9216
	ds_read_b128 v[100:103], v0 offset:9472
	s_waitcnt lgkmcnt(9)
	v_fmac_f32_dpp v104, -v129, v108 row_newbcast:0 row_mask:0xf bank_mask:0xf
	v_mul_f32_dpp v141, v129, v108 row_newbcast:4 row_mask:0xf bank_mask:0xf
	v_mul_f32_e32 v138, s77, v104
	v_mul_f32_dpp v139, v129, v108 row_newbcast:8 row_mask:0xf bank_mask:0xf
	v_fmac_f32_e32 v141, s79, v138
	v_mul_f32_dpp v143, v129, v108 row_newbcast:12 row_mask:0xf bank_mask:0xf
	v_fma_f32 v105, -s80, v141, v105
	v_mul_f32_e32 v144, s80, v138
	v_mul_f32_e32 v140, s81, v105
	v_fmac_f32_e32 v139, s78, v138
	v_pk_fma_f32 v[2:3], v[56:57], v[144:145], v[2:3] op_sel_hi:[1,0,1]
	v_fmac_f32_e32 v143, s83, v138
	v_pk_fma_f32 v[4:5], v[58:59], v[144:145], v[4:5] op_sel_hi:[1,0,1]
	v_pk_fma_f32 v[6:7], v[60:61], v[144:145], v[6:7] op_sel_hi:[1,0,1]
	v_pk_fma_f32 v[8:9], v[62:63], v[144:145], v[8:9] op_sel_hi:[1,0,1]
	v_pk_fma_f32 v[2:3], v[64:65], v[140:141], v[2:3] op_sel_hi:[1,0,1]
	v_pk_fma_f32 v[4:5], v[66:67], v[140:141], v[4:5] op_sel_hi:[1,0,1]
	v_pk_fma_f32 v[6:7], v[68:69], v[140:141], v[6:7] op_sel_hi:[1,0,1]
	v_pk_fma_f32 v[8:9], v[70:71], v[140:141], v[8:9] op_sel_hi:[1,0,1]
	s_waitcnt lgkmcnt(0)
	s_load_dwordx8 s[4:11], s[96:97], 0x60
	v_mov_b32_e32 v108, s88
	v_pk_mul_f32 v[124:125], v[2:3], v[72:73]
	v_mul_f32_e32 v143, s80, v143
	v_pk_mul_f32 v[126:127], v[2:3], v[88:89]
	v_fmac_f32_e32 v143, s82, v140
	v_pk_mul_f32 v[128:129], v[2:3], v[80:81]
	ds_write2_b32 v54, v139, v143 offset0:0 offset1:16
	v_pk_mul_f32 v[134:135], v[2:3], v[96:97]
	ds_read_b128 v[56:59], v0 offset:10240
	v_pk_fma_f32 v[124:125], v[4:5], v[74:75], v[124:125]
	ds_read_b128 v[60:63], v0 offset:10496
	v_pk_fma_f32 v[126:127], v[4:5], v[90:91], v[126:127]
	ds_read_b128 v[64:67], v0 offset:11776
	v_pk_fma_f32 v[128:129], v[4:5], v[82:83], v[128:129]
	ds_read_b128 v[68:71], v0 offset:12032
	v_pk_fma_f32 v[134:135], v[4:5], v[98:99], v[134:135]
	ds_read2st64_b32 v[104:105], v43 offset0:44 offset1:50
	v_pk_fma_f32 v[124:125], v[6:7], v[76:77], v[124:125]
	v_pk_fma_f32 v[126:127], v[6:7], v[92:93], v[126:127]
	v_pk_fma_f32 v[128:129], v[6:7], v[84:85], v[128:129]
	v_pk_fma_f32 v[134:135], v[6:7], v[100:101], v[134:135]
	v_pk_fma_f32 v[124:125], v[8:9], v[78:79], v[124:125]
	v_pk_fma_f32 v[126:127], v[8:9], v[94:95], v[126:127]
	v_pk_fma_f32 v[128:129], v[8:9], v[86:87], v[128:129]
	v_pk_fma_f32 v[134:135], v[8:9], v[102:103], v[134:135]
	v_add_f32_e32 v124, v124, v125
	v_add_f32_e32 v126, v126, v127
	v_add_f32_e32 v128, v128, v129
	v_add_f32_e32 v134, v134, v135
	v_mul_f32_e32 v142, s92, v108
	v_add_f32_dpp v125, v124, v124 row_mirror row_mask:0xf bank_mask:0xf
	v_add_f32_dpp v125, v126, v126 row_mirror row_mask:0xf bank_mask:0xc
	v_add_f32_dpp v127, v128, v128 row_mirror row_mask:0xf bank_mask:0xf
	v_add_f32_dpp v127, v134, v134 row_mirror row_mask:0xf bank_mask:0xc
	v_add_f32_dpp v129, v125, v125 row_half_mirror row_mask:0xf bank_mask:0xf
	v_pk_mul_f32 v[2:3], v[2:3], v[142:143] op_sel_hi:[1,0]
	v_pk_mul_f32 v[4:5], v[4:5], v[142:143] op_sel_hi:[1,0]
	v_add_f32_dpp v129, v127, v127 row_half_mirror row_mask:0xf bank_mask:0xa
	v_pk_mul_f32 v[6:7], v[6:7], v[142:143] op_sel_hi:[1,0]
	v_pk_mul_f32 v[8:9], v[8:9], v[142:143] op_sel_hi:[1,0]
	v_add_f32_dpp v129, v129, v129 quad_perm:[1,0,3,2] row_mask:0xf bank_mask:0xf
	ds_read_b128 v[88:91], v0 offset:10752
	ds_read_b128 v[92:95], v0 offset:11008
	v_add_f32_dpp v129, v129, v129 quad_perm:[2,3,0,1] row_mask:0xf bank_mask:0xf
	ds_read_b128 v[96:99], v0 offset:12288
	ds_read_b128 v[100:103], v0 offset:12544
	v_fmac_f32_dpp v106, -v129, v108 row_newbcast:0 row_mask:0xf bank_mask:0xf
	v_mul_f32_dpp v141, v129, v108 row_newbcast:4 row_mask:0xf bank_mask:0xf
	v_mul_f32_e32 v138, s89, v106
	v_mul_f32_dpp v139, v129, v108 row_newbcast:8 row_mask:0xf bank_mask:0xf
	v_fmac_f32_e32 v141, s91, v138
	v_mul_f32_dpp v143, v129, v108 row_newbcast:12 row_mask:0xf bank_mask:0xf
	v_fma_f32 v107, -s92, v141, v107
	v_mul_f32_e32 v144, s92, v138
	v_mul_f32_e32 v140, s93, v107
	v_fmac_f32_e32 v139, s90, v138
	v_pk_fma_f32 v[2:3], v[72:73], v[144:145], v[2:3] op_sel_hi:[1,0,1]
	v_fmac_f32_e32 v143, s95, v138
	v_pk_fma_f32 v[4:5], v[74:75], v[144:145], v[4:5] op_sel_hi:[1,0,1]
	v_pk_fma_f32 v[6:7], v[76:77], v[144:145], v[6:7] op_sel_hi:[1,0,1]
	v_pk_fma_f32 v[8:9], v[78:79], v[144:145], v[8:9] op_sel_hi:[1,0,1]
	v_pk_fma_f32 v[2:3], v[80:81], v[140:141], v[2:3] op_sel_hi:[1,0,1]
	v_pk_fma_f32 v[4:5], v[82:83], v[140:141], v[4:5] op_sel_hi:[1,0,1]
	v_pk_fma_f32 v[6:7], v[84:85], v[140:141], v[6:7] op_sel_hi:[1,0,1]
	v_pk_fma_f32 v[8:9], v[86:87], v[140:141], v[8:9] op_sel_hi:[1,0,1]
	s_waitcnt lgkmcnt(0)
	s_load_dwordx8 s[76:83], s[96:97], 0x80
	v_mov_b32_e32 v108, s28
	v_pk_mul_f32 v[124:125], v[2:3], v[56:57]
	v_mul_f32_e32 v143, s92, v143
	v_pk_mul_f32 v[126:127], v[2:3], v[88:89]
	v_fmac_f32_e32 v143, s94, v140
	v_pk_mul_f32 v[128:129], v[2:3], v[64:65]
	ds_write2_b32 v54, v139, v143 offset0:32 offset1:48
	v_pk_mul_f32 v[134:135], v[2:3], v[96:97]
	ds_read_b128 v[72:75], v0 offset:13312
	v_pk_fma_f32 v[124:125], v[4:5], v[58:59], v[124:125]
	ds_read_b128 v[76:79], v0 offset:13568
	v_pk_fma_f32 v[126:127], v[4:5], v[90:91], v[126:127]
	ds_read_b128 v[80:83], v0 offset:14848
	v_pk_fma_f32 v[128:129], v[4:5], v[66:67], v[128:129]
	ds_read_b128 v[84:87], v0 offset:15104
	v_pk_fma_f32 v[134:135], v[4:5], v[98:99], v[134:135]
	ds_read2st64_b32 v[106:107], v43 offset0:56 offset1:62
	v_pk_fma_f32 v[124:125], v[6:7], v[60:61], v[124:125]
	v_pk_fma_f32 v[126:127], v[6:7], v[92:93], v[126:127]
	v_pk_fma_f32 v[128:129], v[6:7], v[68:69], v[128:129]
	v_pk_fma_f32 v[134:135], v[6:7], v[100:101], v[134:135]
	v_pk_fma_f32 v[124:125], v[8:9], v[62:63], v[124:125]
	v_pk_fma_f32 v[126:127], v[8:9], v[94:95], v[126:127]
	v_pk_fma_f32 v[128:129], v[8:9], v[70:71], v[128:129]
	v_pk_fma_f32 v[134:135], v[8:9], v[102:103], v[134:135]
	v_add_f32_e32 v124, v124, v125
	v_add_f32_e32 v126, v126, v127
	v_add_f32_e32 v128, v128, v129
	v_add_f32_e32 v134, v134, v135
	v_mul_f32_e32 v142, s32, v108
	v_add_f32_dpp v125, v124, v124 row_mirror row_mask:0xf bank_mask:0xf
	v_add_f32_dpp v125, v126, v126 row_mirror row_mask:0xf bank_mask:0xc
	v_add_f32_dpp v127, v128, v128 row_mirror row_mask:0xf bank_mask:0xf
	v_add_f32_dpp v127, v134, v134 row_mirror row_mask:0xf bank_mask:0xc
	v_add_f32_dpp v129, v125, v125 row_half_mirror row_mask:0xf bank_mask:0xf
	v_pk_mul_f32 v[2:3], v[2:3], v[142:143] op_sel_hi:[1,0]
	v_pk_mul_f32 v[4:5], v[4:5], v[142:143] op_sel_hi:[1,0]
	v_add_f32_dpp v129, v127, v127 row_half_mirror row_mask:0xf bank_mask:0xa
	v_pk_mul_f32 v[6:7], v[6:7], v[142:143] op_sel_hi:[1,0]
	v_pk_mul_f32 v[8:9], v[8:9], v[142:143] op_sel_hi:[1,0]
	v_add_f32_dpp v129, v129, v129 quad_perm:[1,0,3,2] row_mask:0xf bank_mask:0xf
	ds_read_b128 v[88:91], v0 offset:13824
	ds_read_b128 v[92:95], v0 offset:14080
	v_add_f32_dpp v129, v129, v129 quad_perm:[2,3,0,1] row_mask:0xf bank_mask:0xf
	ds_read_b128 v[96:99], v0 offset:15360
	ds_read_b128 v[100:103], v0 offset:15616
	v_fmac_f32_dpp v104, -v129, v108 row_newbcast:0 row_mask:0xf bank_mask:0xf
	v_mul_f32_dpp v141, v129, v108 row_newbcast:4 row_mask:0xf bank_mask:0xf
	v_mul_f32_e32 v138, s29, v104
	v_mul_f32_dpp v139, v129, v108 row_newbcast:8 row_mask:0xf bank_mask:0xf
	v_fmac_f32_e32 v141, s31, v138
	v_mul_f32_dpp v143, v129, v108 row_newbcast:12 row_mask:0xf bank_mask:0xf
	v_fma_f32 v105, -s32, v141, v105
	v_mul_f32_e32 v144, s32, v138
	v_mul_f32_e32 v140, s33, v105
	v_fmac_f32_e32 v139, s30, v138
	v_pk_fma_f32 v[2:3], v[56:57], v[144:145], v[2:3] op_sel_hi:[1,0,1]
	v_fmac_f32_e32 v143, s35, v138
	v_pk_fma_f32 v[4:5], v[58:59], v[144:145], v[4:5] op_sel_hi:[1,0,1]
	v_pk_fma_f32 v[6:7], v[60:61], v[144:145], v[6:7] op_sel_hi:[1,0,1]
	v_pk_fma_f32 v[8:9], v[62:63], v[144:145], v[8:9] op_sel_hi:[1,0,1]
	v_pk_fma_f32 v[2:3], v[64:65], v[140:141], v[2:3] op_sel_hi:[1,0,1]
	v_pk_fma_f32 v[4:5], v[66:67], v[140:141], v[4:5] op_sel_hi:[1,0,1]
	v_pk_fma_f32 v[6:7], v[68:69], v[140:141], v[6:7] op_sel_hi:[1,0,1]
	v_pk_fma_f32 v[8:9], v[70:71], v[140:141], v[8:9] op_sel_hi:[1,0,1]
	s_waitcnt lgkmcnt(0)
	s_load_dwordx8 s[88:95], s[96:97], 0xa0
	v_mov_b32_e32 v108, s4
	v_pk_mul_f32 v[124:125], v[2:3], v[72:73]
	v_mul_f32_e32 v143, s32, v143
	v_pk_mul_f32 v[126:127], v[2:3], v[88:89]
	v_fmac_f32_e32 v143, s34, v140
	v_pk_mul_f32 v[128:129], v[2:3], v[80:81]
	ds_write2_b32 v54, v139, v143 offset0:64 offset1:80
	v_pk_mul_f32 v[134:135], v[2:3], v[96:97]
	ds_read_b128 v[56:59], v0 offset:16384
	v_pk_fma_f32 v[124:125], v[4:5], v[74:75], v[124:125]
	ds_read_b128 v[60:63], v0 offset:16640
	v_pk_fma_f32 v[126:127], v[4:5], v[90:91], v[126:127]
	ds_read_b128 v[64:67], v0 offset:17920
	v_pk_fma_f32 v[128:129], v[4:5], v[82:83], v[128:129]
	ds_read_b128 v[68:71], v0 offset:18176
	v_pk_fma_f32 v[134:135], v[4:5], v[98:99], v[134:135]
	ds_read2st64_b32 v[104:105], v43 offset0:68 offset1:74
	v_pk_fma_f32 v[124:125], v[6:7], v[76:77], v[124:125]
	v_pk_fma_f32 v[126:127], v[6:7], v[92:93], v[126:127]
	v_pk_fma_f32 v[128:129], v[6:7], v[84:85], v[128:129]
	v_pk_fma_f32 v[134:135], v[6:7], v[100:101], v[134:135]
	v_pk_fma_f32 v[124:125], v[8:9], v[78:79], v[124:125]
	v_pk_fma_f32 v[126:127], v[8:9], v[94:95], v[126:127]
	v_pk_fma_f32 v[128:129], v[8:9], v[86:87], v[128:129]
	v_pk_fma_f32 v[134:135], v[8:9], v[102:103], v[134:135]
	v_add_f32_e32 v124, v124, v125
	v_add_f32_e32 v126, v126, v127
	v_add_f32_e32 v128, v128, v129
	v_add_f32_e32 v134, v134, v135
	v_mul_f32_e32 v142, s8, v108
	v_add_f32_dpp v125, v124, v124 row_mirror row_mask:0xf bank_mask:0xf
	v_add_f32_dpp v125, v126, v126 row_mirror row_mask:0xf bank_mask:0xc
	v_add_f32_dpp v127, v128, v128 row_mirror row_mask:0xf bank_mask:0xf
	v_add_f32_dpp v127, v134, v134 row_mirror row_mask:0xf bank_mask:0xc
	v_add_f32_dpp v129, v125, v125 row_half_mirror row_mask:0xf bank_mask:0xf
	v_pk_mul_f32 v[2:3], v[2:3], v[142:143] op_sel_hi:[1,0]
	v_pk_mul_f32 v[4:5], v[4:5], v[142:143] op_sel_hi:[1,0]
	v_add_f32_dpp v129, v127, v127 row_half_mirror row_mask:0xf bank_mask:0xa
	v_pk_mul_f32 v[6:7], v[6:7], v[142:143] op_sel_hi:[1,0]
	v_pk_mul_f32 v[8:9], v[8:9], v[142:143] op_sel_hi:[1,0]
	v_add_f32_dpp v129, v129, v129 quad_perm:[1,0,3,2] row_mask:0xf bank_mask:0xf
	ds_read_b128 v[88:91], v0 offset:16896
	ds_read_b128 v[92:95], v0 offset:17152
	v_add_f32_dpp v129, v129, v129 quad_perm:[2,3,0,1] row_mask:0xf bank_mask:0xf
	ds_read_b128 v[96:99], v0 offset:18432
	ds_read_b128 v[100:103], v0 offset:18688
	v_fmac_f32_dpp v106, -v129, v108 row_newbcast:0 row_mask:0xf bank_mask:0xf
	v_mul_f32_dpp v141, v129, v108 row_newbcast:4 row_mask:0xf bank_mask:0xf
	v_mul_f32_e32 v138, s5, v106
	v_mul_f32_dpp v139, v129, v108 row_newbcast:8 row_mask:0xf bank_mask:0xf
	v_fmac_f32_e32 v141, s7, v138
	v_mul_f32_dpp v143, v129, v108 row_newbcast:12 row_mask:0xf bank_mask:0xf
	v_fma_f32 v107, -s8, v141, v107
	v_mul_f32_e32 v144, s8, v138
	v_mul_f32_e32 v140, s9, v107
	v_fmac_f32_e32 v139, s6, v138
	v_pk_fma_f32 v[2:3], v[72:73], v[144:145], v[2:3] op_sel_hi:[1,0,1]
	v_fmac_f32_e32 v143, s11, v138
	v_pk_fma_f32 v[4:5], v[74:75], v[144:145], v[4:5] op_sel_hi:[1,0,1]
	v_pk_fma_f32 v[6:7], v[76:77], v[144:145], v[6:7] op_sel_hi:[1,0,1]
	v_pk_fma_f32 v[8:9], v[78:79], v[144:145], v[8:9] op_sel_hi:[1,0,1]
	v_pk_fma_f32 v[2:3], v[80:81], v[140:141], v[2:3] op_sel_hi:[1,0,1]
	v_pk_fma_f32 v[4:5], v[82:83], v[140:141], v[4:5] op_sel_hi:[1,0,1]
	v_pk_fma_f32 v[6:7], v[84:85], v[140:141], v[6:7] op_sel_hi:[1,0,1]
	v_pk_fma_f32 v[8:9], v[86:87], v[140:141], v[8:9] op_sel_hi:[1,0,1]
	s_waitcnt lgkmcnt(0)
	s_load_dwordx8 s[28:35], s[96:97], 0xc0
	v_mov_b32_e32 v108, s76
	v_pk_mul_f32 v[124:125], v[2:3], v[56:57]
	v_mul_f32_e32 v143, s8, v143
	v_pk_mul_f32 v[126:127], v[2:3], v[88:89]
	v_fmac_f32_e32 v143, s10, v140
	v_pk_mul_f32 v[128:129], v[2:3], v[64:65]
	ds_write2_b32 v54, v139, v143 offset0:96 offset1:112
	v_pk_mul_f32 v[134:135], v[2:3], v[96:97]
	ds_read_b128 v[72:75], v0 offset:19456
	v_pk_fma_f32 v[124:125], v[4:5], v[58:59], v[124:125]
	ds_read_b128 v[76:79], v0 offset:19712
	v_pk_fma_f32 v[126:127], v[4:5], v[90:91], v[126:127]
	ds_read_b128 v[80:83], v0 offset:20992
	v_pk_fma_f32 v[128:129], v[4:5], v[66:67], v[128:129]
	ds_read_b128 v[84:87], v0 offset:21248
	v_pk_fma_f32 v[134:135], v[4:5], v[98:99], v[134:135]
	ds_read2st64_b32 v[106:107], v43 offset0:80 offset1:86
	v_pk_fma_f32 v[124:125], v[6:7], v[60:61], v[124:125]
	v_pk_fma_f32 v[126:127], v[6:7], v[92:93], v[126:127]
	v_pk_fma_f32 v[128:129], v[6:7], v[68:69], v[128:129]
	v_pk_fma_f32 v[134:135], v[6:7], v[100:101], v[134:135]
	v_pk_fma_f32 v[124:125], v[8:9], v[62:63], v[124:125]
	v_pk_fma_f32 v[126:127], v[8:9], v[94:95], v[126:127]
	v_pk_fma_f32 v[128:129], v[8:9], v[70:71], v[128:129]
	v_pk_fma_f32 v[134:135], v[8:9], v[102:103], v[134:135]
	v_add_f32_e32 v124, v124, v125
	v_add_f32_e32 v126, v126, v127
	v_add_f32_e32 v128, v128, v129
	v_add_f32_e32 v134, v134, v135
	v_mul_f32_e32 v142, s80, v108
	v_add_f32_dpp v125, v124, v124 row_mirror row_mask:0xf bank_mask:0xf
	v_add_f32_dpp v125, v126, v126 row_mirror row_mask:0xf bank_mask:0xc
	v_add_f32_dpp v127, v128, v128 row_mirror row_mask:0xf bank_mask:0xf
	v_add_f32_dpp v127, v134, v134 row_mirror row_mask:0xf bank_mask:0xc
	v_add_f32_dpp v129, v125, v125 row_half_mirror row_mask:0xf bank_mask:0xf
	v_pk_mul_f32 v[2:3], v[2:3], v[142:143] op_sel_hi:[1,0]
	v_pk_mul_f32 v[4:5], v[4:5], v[142:143] op_sel_hi:[1,0]
	v_add_f32_dpp v129, v127, v127 row_half_mirror row_mask:0xf bank_mask:0xa
	v_pk_mul_f32 v[6:7], v[6:7], v[142:143] op_sel_hi:[1,0]
	v_pk_mul_f32 v[8:9], v[8:9], v[142:143] op_sel_hi:[1,0]
	v_add_f32_dpp v129, v129, v129 quad_perm:[1,0,3,2] row_mask:0xf bank_mask:0xf
	ds_read_b128 v[88:91], v0 offset:19968
	ds_read_b128 v[92:95], v0 offset:20224
	v_add_f32_dpp v129, v129, v129 quad_perm:[2,3,0,1] row_mask:0xf bank_mask:0xf
	ds_read_b128 v[96:99], v0 offset:21504
	ds_read_b128 v[100:103], v0 offset:21760
	v_fmac_f32_dpp v104, -v129, v108 row_newbcast:0 row_mask:0xf bank_mask:0xf
	v_mul_f32_dpp v141, v129, v108 row_newbcast:4 row_mask:0xf bank_mask:0xf
	v_mul_f32_e32 v138, s77, v104
	v_mul_f32_dpp v139, v129, v108 row_newbcast:8 row_mask:0xf bank_mask:0xf
	v_fmac_f32_e32 v141, s79, v138
	v_mul_f32_dpp v143, v129, v108 row_newbcast:12 row_mask:0xf bank_mask:0xf
	v_fma_f32 v105, -s80, v141, v105
	v_mul_f32_e32 v144, s80, v138
	v_mul_f32_e32 v140, s81, v105
	v_fmac_f32_e32 v139, s78, v138
	v_pk_fma_f32 v[2:3], v[56:57], v[144:145], v[2:3] op_sel_hi:[1,0,1]
	v_fmac_f32_e32 v143, s83, v138
	v_pk_fma_f32 v[4:5], v[58:59], v[144:145], v[4:5] op_sel_hi:[1,0,1]
	v_pk_fma_f32 v[6:7], v[60:61], v[144:145], v[6:7] op_sel_hi:[1,0,1]
	v_pk_fma_f32 v[8:9], v[62:63], v[144:145], v[8:9] op_sel_hi:[1,0,1]
	v_pk_fma_f32 v[2:3], v[64:65], v[140:141], v[2:3] op_sel_hi:[1,0,1]
	v_pk_fma_f32 v[4:5], v[66:67], v[140:141], v[4:5] op_sel_hi:[1,0,1]
	v_pk_fma_f32 v[6:7], v[68:69], v[140:141], v[6:7] op_sel_hi:[1,0,1]
	v_pk_fma_f32 v[8:9], v[70:71], v[140:141], v[8:9] op_sel_hi:[1,0,1]
	s_waitcnt lgkmcnt(0)
	s_load_dwordx8 s[4:11], s[96:97], 0xe0
	v_mov_b32_e32 v108, s88
	v_pk_mul_f32 v[124:125], v[2:3], v[72:73]
	v_mul_f32_e32 v143, s80, v143
	v_pk_mul_f32 v[126:127], v[2:3], v[88:89]
	v_fmac_f32_e32 v143, s82, v140
	v_pk_mul_f32 v[128:129], v[2:3], v[80:81]
	ds_write2_b32 v54, v139, v143 offset0:128 offset1:144
	v_pk_mul_f32 v[134:135], v[2:3], v[96:97]
	ds_read_b128 v[56:59], v0 offset:22528
	v_pk_fma_f32 v[124:125], v[4:5], v[74:75], v[124:125]
	ds_read_b128 v[60:63], v0 offset:22784
	v_pk_fma_f32 v[126:127], v[4:5], v[90:91], v[126:127]
	ds_read_b128 v[64:67], v0 offset:24064
	v_pk_fma_f32 v[128:129], v[4:5], v[82:83], v[128:129]
	ds_read_b128 v[68:71], v0 offset:24320
	v_pk_fma_f32 v[134:135], v[4:5], v[98:99], v[134:135]
	ds_read2st64_b32 v[104:105], v43 offset0:92 offset1:98
	v_pk_fma_f32 v[124:125], v[6:7], v[76:77], v[124:125]
	v_pk_fma_f32 v[126:127], v[6:7], v[92:93], v[126:127]
	v_pk_fma_f32 v[128:129], v[6:7], v[84:85], v[128:129]
	v_pk_fma_f32 v[134:135], v[6:7], v[100:101], v[134:135]
	v_pk_fma_f32 v[124:125], v[8:9], v[78:79], v[124:125]
	v_pk_fma_f32 v[126:127], v[8:9], v[94:95], v[126:127]
	v_pk_fma_f32 v[128:129], v[8:9], v[86:87], v[128:129]
	v_pk_fma_f32 v[134:135], v[8:9], v[102:103], v[134:135]
	v_add_f32_e32 v124, v124, v125
	v_add_f32_e32 v126, v126, v127
	v_add_f32_e32 v128, v128, v129
	v_add_f32_e32 v134, v134, v135
	v_mul_f32_e32 v142, s92, v108
	v_add_f32_dpp v125, v124, v124 row_mirror row_mask:0xf bank_mask:0xf
	v_add_f32_dpp v125, v126, v126 row_mirror row_mask:0xf bank_mask:0xc
	v_add_f32_dpp v127, v128, v128 row_mirror row_mask:0xf bank_mask:0xf
	v_add_f32_dpp v127, v134, v134 row_mirror row_mask:0xf bank_mask:0xc
	v_add_f32_dpp v129, v125, v125 row_half_mirror row_mask:0xf bank_mask:0xf
	v_pk_mul_f32 v[2:3], v[2:3], v[142:143] op_sel_hi:[1,0]
	v_pk_mul_f32 v[4:5], v[4:5], v[142:143] op_sel_hi:[1,0]
	v_add_f32_dpp v129, v127, v127 row_half_mirror row_mask:0xf bank_mask:0xa
	v_pk_mul_f32 v[6:7], v[6:7], v[142:143] op_sel_hi:[1,0]
	v_pk_mul_f32 v[8:9], v[8:9], v[142:143] op_sel_hi:[1,0]
	v_add_f32_dpp v129, v129, v129 quad_perm:[1,0,3,2] row_mask:0xf bank_mask:0xf
	ds_read_b128 v[88:91], v0 offset:23040
	ds_read_b128 v[92:95], v0 offset:23296
	v_add_f32_dpp v129, v129, v129 quad_perm:[2,3,0,1] row_mask:0xf bank_mask:0xf
	ds_read_b128 v[96:99], v0 offset:24576
	ds_read_b128 v[100:103], v0 offset:24832
	v_fmac_f32_dpp v106, -v129, v108 row_newbcast:0 row_mask:0xf bank_mask:0xf
	v_mul_f32_dpp v141, v129, v108 row_newbcast:4 row_mask:0xf bank_mask:0xf
	v_mul_f32_e32 v138, s89, v106
	v_mul_f32_dpp v139, v129, v108 row_newbcast:8 row_mask:0xf bank_mask:0xf
	v_fmac_f32_e32 v141, s91, v138
	v_mul_f32_dpp v143, v129, v108 row_newbcast:12 row_mask:0xf bank_mask:0xf
	v_fma_f32 v107, -s92, v141, v107
	v_mul_f32_e32 v144, s92, v138
	v_mul_f32_e32 v140, s93, v107
	v_fmac_f32_e32 v139, s90, v138
	v_pk_fma_f32 v[2:3], v[72:73], v[144:145], v[2:3] op_sel_hi:[1,0,1]
	v_fmac_f32_e32 v143, s95, v138
	v_pk_fma_f32 v[4:5], v[74:75], v[144:145], v[4:5] op_sel_hi:[1,0,1]
	v_pk_fma_f32 v[6:7], v[76:77], v[144:145], v[6:7] op_sel_hi:[1,0,1]
	v_pk_fma_f32 v[8:9], v[78:79], v[144:145], v[8:9] op_sel_hi:[1,0,1]
	v_pk_fma_f32 v[2:3], v[80:81], v[140:141], v[2:3] op_sel_hi:[1,0,1]
	v_pk_fma_f32 v[4:5], v[82:83], v[140:141], v[4:5] op_sel_hi:[1,0,1]
	v_pk_fma_f32 v[6:7], v[84:85], v[140:141], v[6:7] op_sel_hi:[1,0,1]
	v_pk_fma_f32 v[8:9], v[86:87], v[140:141], v[8:9] op_sel_hi:[1,0,1]
	s_waitcnt lgkmcnt(0)
	s_load_dwordx8 s[76:83], s[96:97], 0x100
	v_mov_b32_e32 v108, s28
	v_pk_mul_f32 v[124:125], v[2:3], v[56:57]
	v_mul_f32_e32 v143, s92, v143
	v_pk_mul_f32 v[126:127], v[2:3], v[88:89]
	v_fmac_f32_e32 v143, s94, v140
	v_pk_mul_f32 v[128:129], v[2:3], v[64:65]
	ds_write2_b32 v54, v139, v143 offset0:160 offset1:176
	v_pk_mul_f32 v[134:135], v[2:3], v[96:97]
	ds_read_b128 v[72:75], v0 offset:25600
	v_pk_fma_f32 v[124:125], v[4:5], v[58:59], v[124:125]
	ds_read_b128 v[76:79], v0 offset:25856
	v_pk_fma_f32 v[126:127], v[4:5], v[90:91], v[126:127]
	ds_read_b128 v[80:83], v0 offset:27136
	v_pk_fma_f32 v[128:129], v[4:5], v[66:67], v[128:129]
	ds_read_b128 v[84:87], v0 offset:27392
	v_pk_fma_f32 v[134:135], v[4:5], v[98:99], v[134:135]
	ds_read2st64_b32 v[106:107], v43 offset0:104 offset1:110
	v_pk_fma_f32 v[124:125], v[6:7], v[60:61], v[124:125]
	v_pk_fma_f32 v[126:127], v[6:7], v[92:93], v[126:127]
	v_pk_fma_f32 v[128:129], v[6:7], v[68:69], v[128:129]
	v_pk_fma_f32 v[134:135], v[6:7], v[100:101], v[134:135]
	v_pk_fma_f32 v[124:125], v[8:9], v[62:63], v[124:125]
	v_pk_fma_f32 v[126:127], v[8:9], v[94:95], v[126:127]
	v_pk_fma_f32 v[128:129], v[8:9], v[70:71], v[128:129]
	v_pk_fma_f32 v[134:135], v[8:9], v[102:103], v[134:135]
	v_add_f32_e32 v124, v124, v125
	v_add_f32_e32 v126, v126, v127
	v_add_f32_e32 v128, v128, v129
	v_add_f32_e32 v134, v134, v135
	v_mul_f32_e32 v142, s32, v108
	v_add_f32_dpp v125, v124, v124 row_mirror row_mask:0xf bank_mask:0xf
	v_add_f32_dpp v125, v126, v126 row_mirror row_mask:0xf bank_mask:0xc
	v_add_f32_dpp v127, v128, v128 row_mirror row_mask:0xf bank_mask:0xf
	v_add_f32_dpp v127, v134, v134 row_mirror row_mask:0xf bank_mask:0xc
	v_add_f32_dpp v129, v125, v125 row_half_mirror row_mask:0xf bank_mask:0xf
	v_pk_mul_f32 v[2:3], v[2:3], v[142:143] op_sel_hi:[1,0]
	v_pk_mul_f32 v[4:5], v[4:5], v[142:143] op_sel_hi:[1,0]
	v_add_f32_dpp v129, v127, v127 row_half_mirror row_mask:0xf bank_mask:0xa
	v_pk_mul_f32 v[6:7], v[6:7], v[142:143] op_sel_hi:[1,0]
	v_pk_mul_f32 v[8:9], v[8:9], v[142:143] op_sel_hi:[1,0]
	v_add_f32_dpp v129, v129, v129 quad_perm:[1,0,3,2] row_mask:0xf bank_mask:0xf
	ds_read_b128 v[88:91], v0 offset:26112
	ds_read_b128 v[92:95], v0 offset:26368
	v_add_f32_dpp v129, v129, v129 quad_perm:[2,3,0,1] row_mask:0xf bank_mask:0xf
	ds_read_b128 v[96:99], v0 offset:27648
	ds_read_b128 v[100:103], v0 offset:27904
	v_fmac_f32_dpp v104, -v129, v108 row_newbcast:0 row_mask:0xf bank_mask:0xf
	v_mul_f32_dpp v141, v129, v108 row_newbcast:4 row_mask:0xf bank_mask:0xf
	v_mul_f32_e32 v138, s29, v104
	v_mul_f32_dpp v139, v129, v108 row_newbcast:8 row_mask:0xf bank_mask:0xf
	v_fmac_f32_e32 v141, s31, v138
	v_mul_f32_dpp v143, v129, v108 row_newbcast:12 row_mask:0xf bank_mask:0xf
	v_fma_f32 v105, -s32, v141, v105
	v_mul_f32_e32 v144, s32, v138
	v_mul_f32_e32 v140, s33, v105
	v_fmac_f32_e32 v139, s30, v138
	v_pk_fma_f32 v[2:3], v[56:57], v[144:145], v[2:3] op_sel_hi:[1,0,1]
	v_fmac_f32_e32 v143, s35, v138
	v_pk_fma_f32 v[4:5], v[58:59], v[144:145], v[4:5] op_sel_hi:[1,0,1]
	v_pk_fma_f32 v[6:7], v[60:61], v[144:145], v[6:7] op_sel_hi:[1,0,1]
	v_pk_fma_f32 v[8:9], v[62:63], v[144:145], v[8:9] op_sel_hi:[1,0,1]
	v_pk_fma_f32 v[2:3], v[64:65], v[140:141], v[2:3] op_sel_hi:[1,0,1]
	v_pk_fma_f32 v[4:5], v[66:67], v[140:141], v[4:5] op_sel_hi:[1,0,1]
	v_pk_fma_f32 v[6:7], v[68:69], v[140:141], v[6:7] op_sel_hi:[1,0,1]
	v_pk_fma_f32 v[8:9], v[70:71], v[140:141], v[8:9] op_sel_hi:[1,0,1]
	s_waitcnt lgkmcnt(0)
	s_load_dwordx8 s[88:95], s[96:97], 0x120
	v_mov_b32_e32 v108, s4
	v_pk_mul_f32 v[124:125], v[2:3], v[72:73]
	v_mul_f32_e32 v143, s32, v143
	v_pk_mul_f32 v[126:127], v[2:3], v[88:89]
	v_fmac_f32_e32 v143, s34, v140
	v_pk_mul_f32 v[128:129], v[2:3], v[80:81]
	ds_write2_b32 v54, v139, v143 offset0:192 offset1:208
	v_pk_mul_f32 v[134:135], v[2:3], v[96:97]
	ds_read_b128 v[56:59], v0 offset:28672
	v_pk_fma_f32 v[124:125], v[4:5], v[74:75], v[124:125]
	ds_read_b128 v[60:63], v0 offset:28928
	v_pk_fma_f32 v[126:127], v[4:5], v[90:91], v[126:127]
	ds_read_b128 v[64:67], v0 offset:30208
	v_pk_fma_f32 v[128:129], v[4:5], v[82:83], v[128:129]
	ds_read_b128 v[68:71], v0 offset:30464
	v_pk_fma_f32 v[134:135], v[4:5], v[98:99], v[134:135]
	ds_read2st64_b32 v[104:105], v43 offset0:116 offset1:122
	v_pk_fma_f32 v[124:125], v[6:7], v[76:77], v[124:125]
	v_pk_fma_f32 v[126:127], v[6:7], v[92:93], v[126:127]
	v_pk_fma_f32 v[128:129], v[6:7], v[84:85], v[128:129]
	v_pk_fma_f32 v[134:135], v[6:7], v[100:101], v[134:135]
	v_pk_fma_f32 v[124:125], v[8:9], v[78:79], v[124:125]
	v_pk_fma_f32 v[126:127], v[8:9], v[94:95], v[126:127]
	v_pk_fma_f32 v[128:129], v[8:9], v[86:87], v[128:129]
	v_pk_fma_f32 v[134:135], v[8:9], v[102:103], v[134:135]
	v_add_f32_e32 v124, v124, v125
	v_add_f32_e32 v126, v126, v127
	v_add_f32_e32 v128, v128, v129
	v_add_f32_e32 v134, v134, v135
	v_mul_f32_e32 v142, s8, v108
	v_add_f32_dpp v125, v124, v124 row_mirror row_mask:0xf bank_mask:0xf
	v_add_f32_dpp v125, v126, v126 row_mirror row_mask:0xf bank_mask:0xc
	v_add_f32_dpp v127, v128, v128 row_mirror row_mask:0xf bank_mask:0xf
	v_add_f32_dpp v127, v134, v134 row_mirror row_mask:0xf bank_mask:0xc
	v_add_f32_dpp v129, v125, v125 row_half_mirror row_mask:0xf bank_mask:0xf
	v_pk_mul_f32 v[2:3], v[2:3], v[142:143] op_sel_hi:[1,0]
	v_pk_mul_f32 v[4:5], v[4:5], v[142:143] op_sel_hi:[1,0]
	v_add_f32_dpp v129, v127, v127 row_half_mirror row_mask:0xf bank_mask:0xa
	v_pk_mul_f32 v[6:7], v[6:7], v[142:143] op_sel_hi:[1,0]
	v_pk_mul_f32 v[8:9], v[8:9], v[142:143] op_sel_hi:[1,0]
	v_add_f32_dpp v129, v129, v129 quad_perm:[1,0,3,2] row_mask:0xf bank_mask:0xf
	ds_read_b128 v[88:91], v0 offset:29184
	ds_read_b128 v[92:95], v0 offset:29440
	v_add_f32_dpp v129, v129, v129 quad_perm:[2,3,0,1] row_mask:0xf bank_mask:0xf
	ds_read_b128 v[96:99], v0 offset:30720
	ds_read_b128 v[100:103], v0 offset:30976
	v_fmac_f32_dpp v106, -v129, v108 row_newbcast:0 row_mask:0xf bank_mask:0xf
	v_mul_f32_dpp v141, v129, v108 row_newbcast:4 row_mask:0xf bank_mask:0xf
	v_mul_f32_e32 v138, s5, v106
	v_mul_f32_dpp v139, v129, v108 row_newbcast:8 row_mask:0xf bank_mask:0xf
	v_fmac_f32_e32 v141, s7, v138
	v_mul_f32_dpp v143, v129, v108 row_newbcast:12 row_mask:0xf bank_mask:0xf
	v_fma_f32 v107, -s8, v141, v107
	v_mul_f32_e32 v144, s8, v138
	v_mul_f32_e32 v140, s9, v107
	v_fmac_f32_e32 v139, s6, v138
	v_pk_fma_f32 v[2:3], v[72:73], v[144:145], v[2:3] op_sel_hi:[1,0,1]
	v_fmac_f32_e32 v143, s11, v138
	v_pk_fma_f32 v[4:5], v[74:75], v[144:145], v[4:5] op_sel_hi:[1,0,1]
	v_pk_fma_f32 v[6:7], v[76:77], v[144:145], v[6:7] op_sel_hi:[1,0,1]
	v_pk_fma_f32 v[8:9], v[78:79], v[144:145], v[8:9] op_sel_hi:[1,0,1]
	v_pk_fma_f32 v[2:3], v[80:81], v[140:141], v[2:3] op_sel_hi:[1,0,1]
	v_pk_fma_f32 v[4:5], v[82:83], v[140:141], v[4:5] op_sel_hi:[1,0,1]
	v_pk_fma_f32 v[6:7], v[84:85], v[140:141], v[6:7] op_sel_hi:[1,0,1]
	v_pk_fma_f32 v[8:9], v[86:87], v[140:141], v[8:9] op_sel_hi:[1,0,1]
	s_waitcnt lgkmcnt(0)
	s_load_dwordx8 s[28:35], s[96:97], 0x140
	v_mov_b32_e32 v108, s76
	v_pk_mul_f32 v[124:125], v[2:3], v[56:57]
	v_mul_f32_e32 v143, s8, v143
	v_pk_mul_f32 v[126:127], v[2:3], v[88:89]
	v_fmac_f32_e32 v143, s10, v140
	v_pk_mul_f32 v[128:129], v[2:3], v[64:65]
	ds_write2_b32 v54, v139, v143 offset0:224 offset1:240
	v_pk_mul_f32 v[134:135], v[2:3], v[96:97]
	ds_read_b128 v[72:75], v0 offset:31744
	v_pk_fma_f32 v[124:125], v[4:5], v[58:59], v[124:125]
	ds_read_b128 v[76:79], v0 offset:32000
	v_pk_fma_f32 v[126:127], v[4:5], v[90:91], v[126:127]
	ds_read_b128 v[80:83], v0 offset:33280
	v_pk_fma_f32 v[128:129], v[4:5], v[66:67], v[128:129]
	ds_read_b128 v[84:87], v0 offset:33536
	v_pk_fma_f32 v[134:135], v[4:5], v[98:99], v[134:135]
	ds_read2st64_b32 v[106:107], v43 offset0:128 offset1:134
	v_pk_fma_f32 v[124:125], v[6:7], v[60:61], v[124:125]
	v_pk_fma_f32 v[126:127], v[6:7], v[92:93], v[126:127]
	v_pk_fma_f32 v[128:129], v[6:7], v[68:69], v[128:129]
	v_pk_fma_f32 v[134:135], v[6:7], v[100:101], v[134:135]
	v_pk_fma_f32 v[124:125], v[8:9], v[62:63], v[124:125]
	v_pk_fma_f32 v[126:127], v[8:9], v[94:95], v[126:127]
	v_pk_fma_f32 v[128:129], v[8:9], v[70:71], v[128:129]
	v_pk_fma_f32 v[134:135], v[8:9], v[102:103], v[134:135]
	v_add_f32_e32 v124, v124, v125
	v_add_f32_e32 v126, v126, v127
	v_add_f32_e32 v128, v128, v129
	v_add_f32_e32 v134, v134, v135
	v_mul_f32_e32 v142, s80, v108
	v_add_f32_dpp v125, v124, v124 row_mirror row_mask:0xf bank_mask:0xf
	v_add_f32_dpp v125, v126, v126 row_mirror row_mask:0xf bank_mask:0xc
	v_add_f32_dpp v127, v128, v128 row_mirror row_mask:0xf bank_mask:0xf
	v_add_f32_dpp v127, v134, v134 row_mirror row_mask:0xf bank_mask:0xc
	v_add_f32_dpp v129, v125, v125 row_half_mirror row_mask:0xf bank_mask:0xf
	v_pk_mul_f32 v[2:3], v[2:3], v[142:143] op_sel_hi:[1,0]
	v_pk_mul_f32 v[4:5], v[4:5], v[142:143] op_sel_hi:[1,0]
	v_add_f32_dpp v129, v127, v127 row_half_mirror row_mask:0xf bank_mask:0xa
	v_pk_mul_f32 v[6:7], v[6:7], v[142:143] op_sel_hi:[1,0]
	v_pk_mul_f32 v[8:9], v[8:9], v[142:143] op_sel_hi:[1,0]
	v_add_f32_dpp v129, v129, v129 quad_perm:[1,0,3,2] row_mask:0xf bank_mask:0xf
	ds_read_b128 v[88:91], v0 offset:32256
	ds_read_b128 v[92:95], v0 offset:32512
	v_add_f32_dpp v129, v129, v129 quad_perm:[2,3,0,1] row_mask:0xf bank_mask:0xf
	ds_read_b128 v[96:99], v0 offset:33792
	ds_read_b128 v[100:103], v0 offset:34048
	v_fmac_f32_dpp v104, -v129, v108 row_newbcast:0 row_mask:0xf bank_mask:0xf
	v_mul_f32_dpp v141, v129, v108 row_newbcast:4 row_mask:0xf bank_mask:0xf
	v_mul_f32_e32 v138, s77, v104
	v_mul_f32_dpp v139, v129, v108 row_newbcast:8 row_mask:0xf bank_mask:0xf
	v_fmac_f32_e32 v141, s79, v138
	v_mul_f32_dpp v143, v129, v108 row_newbcast:12 row_mask:0xf bank_mask:0xf
	v_fma_f32 v105, -s80, v141, v105
	v_mul_f32_e32 v144, s80, v138
	v_mul_f32_e32 v140, s81, v105
	v_fmac_f32_e32 v139, s78, v138
	v_pk_fma_f32 v[2:3], v[56:57], v[144:145], v[2:3] op_sel_hi:[1,0,1]
	v_fmac_f32_e32 v143, s83, v138
	v_pk_fma_f32 v[4:5], v[58:59], v[144:145], v[4:5] op_sel_hi:[1,0,1]
	v_pk_fma_f32 v[6:7], v[60:61], v[144:145], v[6:7] op_sel_hi:[1,0,1]
	v_pk_fma_f32 v[8:9], v[62:63], v[144:145], v[8:9] op_sel_hi:[1,0,1]
	v_pk_fma_f32 v[2:3], v[64:65], v[140:141], v[2:3] op_sel_hi:[1,0,1]
	v_pk_fma_f32 v[4:5], v[66:67], v[140:141], v[4:5] op_sel_hi:[1,0,1]
	v_pk_fma_f32 v[6:7], v[68:69], v[140:141], v[6:7] op_sel_hi:[1,0,1]
	v_pk_fma_f32 v[8:9], v[70:71], v[140:141], v[8:9] op_sel_hi:[1,0,1]
	s_waitcnt lgkmcnt(0)
	s_load_dwordx8 s[4:11], s[96:97], 0x160
	v_mov_b32_e32 v108, s88
	v_pk_mul_f32 v[124:125], v[2:3], v[72:73]
	v_mul_f32_e32 v143, s80, v143
	v_pk_mul_f32 v[126:127], v[2:3], v[88:89]
	v_fmac_f32_e32 v143, s82, v140
	v_pk_mul_f32 v[128:129], v[2:3], v[80:81]
	ds_write2_b32 v55, v139, v143 offset0:0 offset1:16
	v_pk_mul_f32 v[134:135], v[2:3], v[96:97]
	ds_read_b128 v[56:59], v0 offset:34816
	v_pk_fma_f32 v[124:125], v[4:5], v[74:75], v[124:125]
	ds_read_b128 v[60:63], v0 offset:35072
	v_pk_fma_f32 v[126:127], v[4:5], v[90:91], v[126:127]
	ds_read_b128 v[64:67], v0 offset:36352
	v_pk_fma_f32 v[128:129], v[4:5], v[82:83], v[128:129]
	ds_read_b128 v[68:71], v0 offset:36608
	v_pk_fma_f32 v[134:135], v[4:5], v[98:99], v[134:135]
	ds_read2st64_b32 v[104:105], v43 offset0:140 offset1:146
	v_pk_fma_f32 v[124:125], v[6:7], v[76:77], v[124:125]
	v_pk_fma_f32 v[126:127], v[6:7], v[92:93], v[126:127]
	v_pk_fma_f32 v[128:129], v[6:7], v[84:85], v[128:129]
	v_pk_fma_f32 v[134:135], v[6:7], v[100:101], v[134:135]
	v_pk_fma_f32 v[124:125], v[8:9], v[78:79], v[124:125]
	v_pk_fma_f32 v[126:127], v[8:9], v[94:95], v[126:127]
	v_pk_fma_f32 v[128:129], v[8:9], v[86:87], v[128:129]
	v_pk_fma_f32 v[134:135], v[8:9], v[102:103], v[134:135]
	v_add_f32_e32 v124, v124, v125
	v_add_f32_e32 v126, v126, v127
	v_add_f32_e32 v128, v128, v129
	v_add_f32_e32 v134, v134, v135
	v_mul_f32_e32 v142, s92, v108
	v_add_f32_dpp v125, v124, v124 row_mirror row_mask:0xf bank_mask:0xf
	v_add_f32_dpp v125, v126, v126 row_mirror row_mask:0xf bank_mask:0xc
	v_add_f32_dpp v127, v128, v128 row_mirror row_mask:0xf bank_mask:0xf
	v_add_f32_dpp v127, v134, v134 row_mirror row_mask:0xf bank_mask:0xc
	v_add_f32_dpp v129, v125, v125 row_half_mirror row_mask:0xf bank_mask:0xf
	v_pk_mul_f32 v[2:3], v[2:3], v[142:143] op_sel_hi:[1,0]
	v_pk_mul_f32 v[4:5], v[4:5], v[142:143] op_sel_hi:[1,0]
	v_add_f32_dpp v129, v127, v127 row_half_mirror row_mask:0xf bank_mask:0xa
	v_pk_mul_f32 v[6:7], v[6:7], v[142:143] op_sel_hi:[1,0]
	v_pk_mul_f32 v[8:9], v[8:9], v[142:143] op_sel_hi:[1,0]
	v_add_f32_dpp v129, v129, v129 quad_perm:[1,0,3,2] row_mask:0xf bank_mask:0xf
	ds_read_b128 v[88:91], v0 offset:35328
	ds_read_b128 v[92:95], v0 offset:35584
	v_add_f32_dpp v129, v129, v129 quad_perm:[2,3,0,1] row_mask:0xf bank_mask:0xf
	ds_read_b128 v[96:99], v0 offset:36864
	ds_read_b128 v[100:103], v0 offset:37120
	v_fmac_f32_dpp v106, -v129, v108 row_newbcast:0 row_mask:0xf bank_mask:0xf
	v_mul_f32_dpp v141, v129, v108 row_newbcast:4 row_mask:0xf bank_mask:0xf
	v_mul_f32_e32 v138, s89, v106
	v_mul_f32_dpp v139, v129, v108 row_newbcast:8 row_mask:0xf bank_mask:0xf
	v_fmac_f32_e32 v141, s91, v138
	v_mul_f32_dpp v143, v129, v108 row_newbcast:12 row_mask:0xf bank_mask:0xf
	v_fma_f32 v107, -s92, v141, v107
	v_mul_f32_e32 v144, s92, v138
	v_mul_f32_e32 v140, s93, v107
	v_fmac_f32_e32 v139, s90, v138
	v_pk_fma_f32 v[2:3], v[72:73], v[144:145], v[2:3] op_sel_hi:[1,0,1]
	v_fmac_f32_e32 v143, s95, v138
	v_pk_fma_f32 v[4:5], v[74:75], v[144:145], v[4:5] op_sel_hi:[1,0,1]
	v_pk_fma_f32 v[6:7], v[76:77], v[144:145], v[6:7] op_sel_hi:[1,0,1]
	v_pk_fma_f32 v[8:9], v[78:79], v[144:145], v[8:9] op_sel_hi:[1,0,1]
	v_pk_fma_f32 v[2:3], v[80:81], v[140:141], v[2:3] op_sel_hi:[1,0,1]
	v_pk_fma_f32 v[4:5], v[82:83], v[140:141], v[4:5] op_sel_hi:[1,0,1]
	v_pk_fma_f32 v[6:7], v[84:85], v[140:141], v[6:7] op_sel_hi:[1,0,1]
	v_pk_fma_f32 v[8:9], v[86:87], v[140:141], v[8:9] op_sel_hi:[1,0,1]
	s_waitcnt lgkmcnt(0)
	s_load_dwordx8 s[76:83], s[96:97], 0x180
	v_mov_b32_e32 v108, s28
	v_pk_mul_f32 v[124:125], v[2:3], v[56:57]
	v_mul_f32_e32 v143, s92, v143
	v_pk_mul_f32 v[126:127], v[2:3], v[88:89]
	v_fmac_f32_e32 v143, s94, v140
	v_pk_mul_f32 v[128:129], v[2:3], v[64:65]
	ds_write2_b32 v55, v139, v143 offset0:32 offset1:48
	v_pk_mul_f32 v[134:135], v[2:3], v[96:97]
	ds_read_b128 v[72:75], v0 offset:37888
	v_pk_fma_f32 v[124:125], v[4:5], v[58:59], v[124:125]
	ds_read_b128 v[76:79], v0 offset:38144
	v_pk_fma_f32 v[126:127], v[4:5], v[90:91], v[126:127]
	ds_read_b128 v[80:83], v0 offset:39424
	v_pk_fma_f32 v[128:129], v[4:5], v[66:67], v[128:129]
	ds_read_b128 v[84:87], v0 offset:39680
	v_pk_fma_f32 v[134:135], v[4:5], v[98:99], v[134:135]
	ds_read2st64_b32 v[106:107], v43 offset0:152 offset1:158
	v_pk_fma_f32 v[124:125], v[6:7], v[60:61], v[124:125]
	v_pk_fma_f32 v[126:127], v[6:7], v[92:93], v[126:127]
	v_pk_fma_f32 v[128:129], v[6:7], v[68:69], v[128:129]
	v_pk_fma_f32 v[134:135], v[6:7], v[100:101], v[134:135]
	v_pk_fma_f32 v[124:125], v[8:9], v[62:63], v[124:125]
	v_pk_fma_f32 v[126:127], v[8:9], v[94:95], v[126:127]
	v_pk_fma_f32 v[128:129], v[8:9], v[70:71], v[128:129]
	v_pk_fma_f32 v[134:135], v[8:9], v[102:103], v[134:135]
	v_add_f32_e32 v124, v124, v125
	v_add_f32_e32 v126, v126, v127
	v_add_f32_e32 v128, v128, v129
	v_add_f32_e32 v134, v134, v135
	v_mul_f32_e32 v142, s32, v108
	v_add_f32_dpp v125, v124, v124 row_mirror row_mask:0xf bank_mask:0xf
	v_add_f32_dpp v125, v126, v126 row_mirror row_mask:0xf bank_mask:0xc
	v_add_f32_dpp v127, v128, v128 row_mirror row_mask:0xf bank_mask:0xf
	v_add_f32_dpp v127, v134, v134 row_mirror row_mask:0xf bank_mask:0xc
	v_add_f32_dpp v129, v125, v125 row_half_mirror row_mask:0xf bank_mask:0xf
	v_pk_mul_f32 v[2:3], v[2:3], v[142:143] op_sel_hi:[1,0]
	v_pk_mul_f32 v[4:5], v[4:5], v[142:143] op_sel_hi:[1,0]
	v_add_f32_dpp v129, v127, v127 row_half_mirror row_mask:0xf bank_mask:0xa
	v_pk_mul_f32 v[6:7], v[6:7], v[142:143] op_sel_hi:[1,0]
	v_pk_mul_f32 v[8:9], v[8:9], v[142:143] op_sel_hi:[1,0]
	v_add_f32_dpp v129, v129, v129 quad_perm:[1,0,3,2] row_mask:0xf bank_mask:0xf
	ds_read_b128 v[88:91], v0 offset:38400
	ds_read_b128 v[92:95], v0 offset:38656
	v_add_f32_dpp v129, v129, v129 quad_perm:[2,3,0,1] row_mask:0xf bank_mask:0xf
	ds_read_b128 v[96:99], v0 offset:39936
	ds_read_b128 v[100:103], v0 offset:40192
	v_fmac_f32_dpp v104, -v129, v108 row_newbcast:0 row_mask:0xf bank_mask:0xf
	v_mul_f32_dpp v141, v129, v108 row_newbcast:4 row_mask:0xf bank_mask:0xf
	v_mul_f32_e32 v138, s29, v104
	v_mul_f32_dpp v139, v129, v108 row_newbcast:8 row_mask:0xf bank_mask:0xf
	v_fmac_f32_e32 v141, s31, v138
	v_mul_f32_dpp v143, v129, v108 row_newbcast:12 row_mask:0xf bank_mask:0xf
	v_fma_f32 v105, -s32, v141, v105
	v_mul_f32_e32 v144, s32, v138
	v_mul_f32_e32 v140, s33, v105
	v_fmac_f32_e32 v139, s30, v138
	v_pk_fma_f32 v[2:3], v[56:57], v[144:145], v[2:3] op_sel_hi:[1,0,1]
	v_fmac_f32_e32 v143, s35, v138
	v_pk_fma_f32 v[4:5], v[58:59], v[144:145], v[4:5] op_sel_hi:[1,0,1]
	v_pk_fma_f32 v[6:7], v[60:61], v[144:145], v[6:7] op_sel_hi:[1,0,1]
	v_pk_fma_f32 v[8:9], v[62:63], v[144:145], v[8:9] op_sel_hi:[1,0,1]
	v_pk_fma_f32 v[2:3], v[64:65], v[140:141], v[2:3] op_sel_hi:[1,0,1]
	v_pk_fma_f32 v[4:5], v[66:67], v[140:141], v[4:5] op_sel_hi:[1,0,1]
	v_pk_fma_f32 v[6:7], v[68:69], v[140:141], v[6:7] op_sel_hi:[1,0,1]
	v_pk_fma_f32 v[8:9], v[70:71], v[140:141], v[8:9] op_sel_hi:[1,0,1]
	s_waitcnt lgkmcnt(0)
	s_load_dwordx8 s[88:95], s[96:97], 0x1a0
	v_mov_b32_e32 v108, s4
	v_pk_mul_f32 v[124:125], v[2:3], v[72:73]
	v_mul_f32_e32 v143, s32, v143
	v_pk_mul_f32 v[126:127], v[2:3], v[88:89]
	v_fmac_f32_e32 v143, s34, v140
	v_pk_mul_f32 v[128:129], v[2:3], v[80:81]
	ds_write2_b32 v55, v139, v143 offset0:64 offset1:80
	v_pk_mul_f32 v[134:135], v[2:3], v[96:97]
	ds_read_b128 v[56:59], v0 offset:40960
	v_pk_fma_f32 v[124:125], v[4:5], v[74:75], v[124:125]
	ds_read_b128 v[60:63], v0 offset:41216
	v_pk_fma_f32 v[126:127], v[4:5], v[90:91], v[126:127]
	ds_read_b128 v[64:67], v0 offset:42496
	v_pk_fma_f32 v[128:129], v[4:5], v[82:83], v[128:129]
	ds_read_b128 v[68:71], v0 offset:42752
	v_pk_fma_f32 v[134:135], v[4:5], v[98:99], v[134:135]
	ds_read2st64_b32 v[104:105], v43 offset0:164 offset1:170
	v_pk_fma_f32 v[124:125], v[6:7], v[76:77], v[124:125]
	v_pk_fma_f32 v[126:127], v[6:7], v[92:93], v[126:127]
	v_pk_fma_f32 v[128:129], v[6:7], v[84:85], v[128:129]
	v_pk_fma_f32 v[134:135], v[6:7], v[100:101], v[134:135]
	v_pk_fma_f32 v[124:125], v[8:9], v[78:79], v[124:125]
	v_pk_fma_f32 v[126:127], v[8:9], v[94:95], v[126:127]
	v_pk_fma_f32 v[128:129], v[8:9], v[86:87], v[128:129]
	v_pk_fma_f32 v[134:135], v[8:9], v[102:103], v[134:135]
	v_add_f32_e32 v124, v124, v125
	v_add_f32_e32 v126, v126, v127
	v_add_f32_e32 v128, v128, v129
	v_add_f32_e32 v134, v134, v135
	v_mul_f32_e32 v142, s8, v108
	v_add_f32_dpp v125, v124, v124 row_mirror row_mask:0xf bank_mask:0xf
	v_add_f32_dpp v125, v126, v126 row_mirror row_mask:0xf bank_mask:0xc
	v_add_f32_dpp v127, v128, v128 row_mirror row_mask:0xf bank_mask:0xf
	v_add_f32_dpp v127, v134, v134 row_mirror row_mask:0xf bank_mask:0xc
	v_add_f32_dpp v129, v125, v125 row_half_mirror row_mask:0xf bank_mask:0xf
	v_pk_mul_f32 v[2:3], v[2:3], v[142:143] op_sel_hi:[1,0]
	v_pk_mul_f32 v[4:5], v[4:5], v[142:143] op_sel_hi:[1,0]
	v_add_f32_dpp v129, v127, v127 row_half_mirror row_mask:0xf bank_mask:0xa
	v_pk_mul_f32 v[6:7], v[6:7], v[142:143] op_sel_hi:[1,0]
	v_pk_mul_f32 v[8:9], v[8:9], v[142:143] op_sel_hi:[1,0]
	v_add_f32_dpp v129, v129, v129 quad_perm:[1,0,3,2] row_mask:0xf bank_mask:0xf
	ds_read_b128 v[88:91], v0 offset:41472
	ds_read_b128 v[92:95], v0 offset:41728
	v_add_f32_dpp v129, v129, v129 quad_perm:[2,3,0,1] row_mask:0xf bank_mask:0xf
	ds_read_b128 v[96:99], v0 offset:43008
	ds_read_b128 v[100:103], v0 offset:43264
	v_fmac_f32_dpp v106, -v129, v108 row_newbcast:0 row_mask:0xf bank_mask:0xf
	v_mul_f32_dpp v141, v129, v108 row_newbcast:4 row_mask:0xf bank_mask:0xf
	v_mul_f32_e32 v138, s5, v106
	v_mul_f32_dpp v139, v129, v108 row_newbcast:8 row_mask:0xf bank_mask:0xf
	v_fmac_f32_e32 v141, s7, v138
	v_mul_f32_dpp v143, v129, v108 row_newbcast:12 row_mask:0xf bank_mask:0xf
	v_fma_f32 v107, -s8, v141, v107
	v_mul_f32_e32 v144, s8, v138
	v_mul_f32_e32 v140, s9, v107
	v_fmac_f32_e32 v139, s6, v138
	v_pk_fma_f32 v[2:3], v[72:73], v[144:145], v[2:3] op_sel_hi:[1,0,1]
	v_fmac_f32_e32 v143, s11, v138
	v_pk_fma_f32 v[4:5], v[74:75], v[144:145], v[4:5] op_sel_hi:[1,0,1]
	v_pk_fma_f32 v[6:7], v[76:77], v[144:145], v[6:7] op_sel_hi:[1,0,1]
	v_pk_fma_f32 v[8:9], v[78:79], v[144:145], v[8:9] op_sel_hi:[1,0,1]
	v_pk_fma_f32 v[2:3], v[80:81], v[140:141], v[2:3] op_sel_hi:[1,0,1]
	v_pk_fma_f32 v[4:5], v[82:83], v[140:141], v[4:5] op_sel_hi:[1,0,1]
	v_pk_fma_f32 v[6:7], v[84:85], v[140:141], v[6:7] op_sel_hi:[1,0,1]
	v_pk_fma_f32 v[8:9], v[86:87], v[140:141], v[8:9] op_sel_hi:[1,0,1]
	s_waitcnt lgkmcnt(0)
	s_load_dwordx8 s[28:35], s[96:97], 0x1c0
	v_mov_b32_e32 v108, s76
	v_pk_mul_f32 v[124:125], v[2:3], v[56:57]
	v_mul_f32_e32 v143, s8, v143
	v_pk_mul_f32 v[126:127], v[2:3], v[88:89]
	v_fmac_f32_e32 v143, s10, v140
	v_pk_mul_f32 v[128:129], v[2:3], v[64:65]
	ds_write2_b32 v55, v139, v143 offset0:96 offset1:112
	v_pk_mul_f32 v[134:135], v[2:3], v[96:97]
	ds_read_b128 v[72:75], v0 offset:44032
	v_pk_fma_f32 v[124:125], v[4:5], v[58:59], v[124:125]
	ds_read_b128 v[76:79], v0 offset:44288
	v_pk_fma_f32 v[126:127], v[4:5], v[90:91], v[126:127]
	ds_read_b128 v[80:83], v0 offset:45568
	v_pk_fma_f32 v[128:129], v[4:5], v[66:67], v[128:129]
	ds_read_b128 v[84:87], v0 offset:45824
	v_pk_fma_f32 v[134:135], v[4:5], v[98:99], v[134:135]
	ds_read2st64_b32 v[106:107], v43 offset0:176 offset1:182
	v_pk_fma_f32 v[124:125], v[6:7], v[60:61], v[124:125]
	v_pk_fma_f32 v[126:127], v[6:7], v[92:93], v[126:127]
	v_pk_fma_f32 v[128:129], v[6:7], v[68:69], v[128:129]
	v_pk_fma_f32 v[134:135], v[6:7], v[100:101], v[134:135]
	v_pk_fma_f32 v[124:125], v[8:9], v[62:63], v[124:125]
	v_pk_fma_f32 v[126:127], v[8:9], v[94:95], v[126:127]
	v_pk_fma_f32 v[128:129], v[8:9], v[70:71], v[128:129]
	v_pk_fma_f32 v[134:135], v[8:9], v[102:103], v[134:135]
	v_add_f32_e32 v124, v124, v125
	v_add_f32_e32 v126, v126, v127
	v_add_f32_e32 v128, v128, v129
	v_add_f32_e32 v134, v134, v135
	v_mul_f32_e32 v142, s80, v108
	v_add_f32_dpp v125, v124, v124 row_mirror row_mask:0xf bank_mask:0xf
	v_add_f32_dpp v125, v126, v126 row_mirror row_mask:0xf bank_mask:0xc
	v_add_f32_dpp v127, v128, v128 row_mirror row_mask:0xf bank_mask:0xf
	v_add_f32_dpp v127, v134, v134 row_mirror row_mask:0xf bank_mask:0xc
	v_add_f32_dpp v129, v125, v125 row_half_mirror row_mask:0xf bank_mask:0xf
	v_pk_mul_f32 v[2:3], v[2:3], v[142:143] op_sel_hi:[1,0]
	v_pk_mul_f32 v[4:5], v[4:5], v[142:143] op_sel_hi:[1,0]
	v_add_f32_dpp v129, v127, v127 row_half_mirror row_mask:0xf bank_mask:0xa
	v_pk_mul_f32 v[6:7], v[6:7], v[142:143] op_sel_hi:[1,0]
	v_pk_mul_f32 v[8:9], v[8:9], v[142:143] op_sel_hi:[1,0]
	v_add_f32_dpp v129, v129, v129 quad_perm:[1,0,3,2] row_mask:0xf bank_mask:0xf
	ds_read_b128 v[88:91], v0 offset:44544
	ds_read_b128 v[92:95], v0 offset:44800
	v_add_f32_dpp v129, v129, v129 quad_perm:[2,3,0,1] row_mask:0xf bank_mask:0xf
	ds_read_b128 v[96:99], v0 offset:46080
	ds_read_b128 v[100:103], v0 offset:46336
	v_fmac_f32_dpp v104, -v129, v108 row_newbcast:0 row_mask:0xf bank_mask:0xf
	v_mul_f32_dpp v141, v129, v108 row_newbcast:4 row_mask:0xf bank_mask:0xf
	v_mul_f32_e32 v138, s77, v104
	v_mul_f32_dpp v139, v129, v108 row_newbcast:8 row_mask:0xf bank_mask:0xf
	v_fmac_f32_e32 v141, s79, v138
	v_mul_f32_dpp v143, v129, v108 row_newbcast:12 row_mask:0xf bank_mask:0xf
	v_fma_f32 v105, -s80, v141, v105
	v_mul_f32_e32 v144, s80, v138
	v_mul_f32_e32 v140, s81, v105
	v_fmac_f32_e32 v139, s78, v138
	v_pk_fma_f32 v[2:3], v[56:57], v[144:145], v[2:3] op_sel_hi:[1,0,1]
	v_fmac_f32_e32 v143, s83, v138
	v_pk_fma_f32 v[4:5], v[58:59], v[144:145], v[4:5] op_sel_hi:[1,0,1]
	v_pk_fma_f32 v[6:7], v[60:61], v[144:145], v[6:7] op_sel_hi:[1,0,1]
	v_pk_fma_f32 v[8:9], v[62:63], v[144:145], v[8:9] op_sel_hi:[1,0,1]
	v_pk_fma_f32 v[2:3], v[64:65], v[140:141], v[2:3] op_sel_hi:[1,0,1]
	v_pk_fma_f32 v[4:5], v[66:67], v[140:141], v[4:5] op_sel_hi:[1,0,1]
	v_pk_fma_f32 v[6:7], v[68:69], v[140:141], v[6:7] op_sel_hi:[1,0,1]
	v_pk_fma_f32 v[8:9], v[70:71], v[140:141], v[8:9] op_sel_hi:[1,0,1]
	s_waitcnt lgkmcnt(0)
	s_load_dwordx8 s[4:11], s[96:97], 0x1e0
	v_mov_b32_e32 v108, s88
	v_pk_mul_f32 v[124:125], v[2:3], v[72:73]
	v_mul_f32_e32 v143, s80, v143
	v_pk_mul_f32 v[126:127], v[2:3], v[88:89]
	v_fmac_f32_e32 v143, s82, v140
	v_pk_mul_f32 v[128:129], v[2:3], v[80:81]
	ds_write2_b32 v55, v139, v143 offset0:128 offset1:144
	v_pk_mul_f32 v[134:135], v[2:3], v[96:97]
	ds_read_b128 v[56:59], v0 offset:47104
	v_pk_fma_f32 v[124:125], v[4:5], v[74:75], v[124:125]
	ds_read_b128 v[60:63], v0 offset:47360
	v_pk_fma_f32 v[126:127], v[4:5], v[90:91], v[126:127]
	ds_read_b128 v[64:67], v0 offset:48640
	v_pk_fma_f32 v[128:129], v[4:5], v[82:83], v[128:129]
	ds_read_b128 v[68:71], v0 offset:48896
	v_pk_fma_f32 v[134:135], v[4:5], v[98:99], v[134:135]
	ds_read2st64_b32 v[104:105], v43 offset0:188 offset1:194
	v_pk_fma_f32 v[124:125], v[6:7], v[76:77], v[124:125]
	v_pk_fma_f32 v[126:127], v[6:7], v[92:93], v[126:127]
	v_pk_fma_f32 v[128:129], v[6:7], v[84:85], v[128:129]
	v_pk_fma_f32 v[134:135], v[6:7], v[100:101], v[134:135]
	v_pk_fma_f32 v[124:125], v[8:9], v[78:79], v[124:125]
	v_pk_fma_f32 v[126:127], v[8:9], v[94:95], v[126:127]
	v_pk_fma_f32 v[128:129], v[8:9], v[86:87], v[128:129]
	v_pk_fma_f32 v[134:135], v[8:9], v[102:103], v[134:135]
	v_add_f32_e32 v124, v124, v125
	v_add_f32_e32 v126, v126, v127
	v_add_f32_e32 v128, v128, v129
	v_add_f32_e32 v134, v134, v135
	v_mul_f32_e32 v142, s92, v108
	v_add_f32_dpp v125, v124, v124 row_mirror row_mask:0xf bank_mask:0xf
	v_add_f32_dpp v125, v126, v126 row_mirror row_mask:0xf bank_mask:0xc
	v_add_f32_dpp v127, v128, v128 row_mirror row_mask:0xf bank_mask:0xf
	v_add_f32_dpp v127, v134, v134 row_mirror row_mask:0xf bank_mask:0xc
	v_add_f32_dpp v129, v125, v125 row_half_mirror row_mask:0xf bank_mask:0xf
	v_pk_mul_f32 v[2:3], v[2:3], v[142:143] op_sel_hi:[1,0]
	v_pk_mul_f32 v[4:5], v[4:5], v[142:143] op_sel_hi:[1,0]
	v_add_f32_dpp v129, v127, v127 row_half_mirror row_mask:0xf bank_mask:0xa
	v_pk_mul_f32 v[6:7], v[6:7], v[142:143] op_sel_hi:[1,0]
	v_pk_mul_f32 v[8:9], v[8:9], v[142:143] op_sel_hi:[1,0]
	v_add_f32_dpp v129, v129, v129 quad_perm:[1,0,3,2] row_mask:0xf bank_mask:0xf
	ds_read_b128 v[88:91], v0 offset:47616
	ds_read_b128 v[92:95], v0 offset:47872
	v_add_f32_dpp v129, v129, v129 quad_perm:[2,3,0,1] row_mask:0xf bank_mask:0xf
	ds_read_b128 v[96:99], v0 offset:49152
	ds_read_b128 v[100:103], v0 offset:49408
	v_fmac_f32_dpp v106, -v129, v108 row_newbcast:0 row_mask:0xf bank_mask:0xf
	v_mul_f32_dpp v141, v129, v108 row_newbcast:4 row_mask:0xf bank_mask:0xf
	v_mul_f32_e32 v138, s89, v106
	v_mul_f32_dpp v139, v129, v108 row_newbcast:8 row_mask:0xf bank_mask:0xf
	v_fmac_f32_e32 v141, s91, v138
	v_mul_f32_dpp v143, v129, v108 row_newbcast:12 row_mask:0xf bank_mask:0xf
	v_fma_f32 v107, -s92, v141, v107
	v_mul_f32_e32 v144, s92, v138
	v_mul_f32_e32 v140, s93, v107
	v_fmac_f32_e32 v139, s90, v138
	v_pk_fma_f32 v[2:3], v[72:73], v[144:145], v[2:3] op_sel_hi:[1,0,1]
	v_fmac_f32_e32 v143, s95, v138
	v_pk_fma_f32 v[4:5], v[74:75], v[144:145], v[4:5] op_sel_hi:[1,0,1]
	v_pk_fma_f32 v[6:7], v[76:77], v[144:145], v[6:7] op_sel_hi:[1,0,1]
	v_pk_fma_f32 v[8:9], v[78:79], v[144:145], v[8:9] op_sel_hi:[1,0,1]
	v_pk_fma_f32 v[2:3], v[80:81], v[140:141], v[2:3] op_sel_hi:[1,0,1]
	v_pk_fma_f32 v[4:5], v[82:83], v[140:141], v[4:5] op_sel_hi:[1,0,1]
	v_pk_fma_f32 v[6:7], v[84:85], v[140:141], v[6:7] op_sel_hi:[1,0,1]
	v_pk_fma_f32 v[8:9], v[86:87], v[140:141], v[8:9] op_sel_hi:[1,0,1]
	s_waitcnt lgkmcnt(0)
	s_add_i32 m0, s39, 1
	s_min_u32 m0, m0, 0x1ff
	s_lshl_b32 m0, m0, 9
	s_add_u32 s96, s100, m0
	s_addc_u32 s97, s101, 0
	s_load_dwordx8 s[76:83], s[96:97], 0x0
	v_mov_b32_e32 v108, s28
	v_pk_mul_f32 v[124:125], v[2:3], v[56:57]
	v_mul_f32_e32 v143, s92, v143
	v_pk_mul_f32 v[126:127], v[2:3], v[88:89]
	v_fmac_f32_e32 v143, s94, v140
	v_pk_mul_f32 v[128:129], v[2:3], v[64:65]
	ds_write2_b32 v55, v139, v143 offset0:160 offset1:176
	v_pk_mul_f32 v[134:135], v[2:3], v[96:97]
	ds_read_b128 v[72:75], v0 offset:50176
	v_pk_fma_f32 v[124:125], v[4:5], v[58:59], v[124:125]
	ds_read_b128 v[76:79], v0 offset:50432
	v_pk_fma_f32 v[126:127], v[4:5], v[90:91], v[126:127]
	ds_read_b128 v[80:83], v0 offset:51712
	v_pk_fma_f32 v[128:129], v[4:5], v[66:67], v[128:129]
	ds_read_b128 v[84:87], v0 offset:51968
	v_pk_fma_f32 v[134:135], v[4:5], v[98:99], v[134:135]
	ds_read2st64_b32 v[106:107], v43 offset0:200 offset1:206
	v_pk_fma_f32 v[124:125], v[6:7], v[60:61], v[124:125]
	v_pk_fma_f32 v[126:127], v[6:7], v[92:93], v[126:127]
	v_pk_fma_f32 v[128:129], v[6:7], v[68:69], v[128:129]
	v_pk_fma_f32 v[134:135], v[6:7], v[100:101], v[134:135]
	v_pk_fma_f32 v[124:125], v[8:9], v[62:63], v[124:125]
	v_pk_fma_f32 v[126:127], v[8:9], v[94:95], v[126:127]
	v_pk_fma_f32 v[128:129], v[8:9], v[70:71], v[128:129]
	v_pk_fma_f32 v[134:135], v[8:9], v[102:103], v[134:135]
	v_add_f32_e32 v124, v124, v125
	v_add_f32_e32 v126, v126, v127
	v_add_f32_e32 v128, v128, v129
	v_add_f32_e32 v134, v134, v135
	v_mul_f32_e32 v142, s32, v108
	v_add_f32_dpp v125, v124, v124 row_mirror row_mask:0xf bank_mask:0xf
	v_add_f32_dpp v125, v126, v126 row_mirror row_mask:0xf bank_mask:0xc
	v_add_f32_dpp v127, v128, v128 row_mirror row_mask:0xf bank_mask:0xf
	v_add_f32_dpp v127, v134, v134 row_mirror row_mask:0xf bank_mask:0xc
	v_add_f32_dpp v129, v125, v125 row_half_mirror row_mask:0xf bank_mask:0xf
	v_pk_mul_f32 v[2:3], v[2:3], v[142:143] op_sel_hi:[1,0]
	v_pk_mul_f32 v[4:5], v[4:5], v[142:143] op_sel_hi:[1,0]
	v_add_f32_dpp v129, v127, v127 row_half_mirror row_mask:0xf bank_mask:0xa
	v_pk_mul_f32 v[6:7], v[6:7], v[142:143] op_sel_hi:[1,0]
	v_pk_mul_f32 v[8:9], v[8:9], v[142:143] op_sel_hi:[1,0]
	v_add_f32_dpp v129, v129, v129 quad_perm:[1,0,3,2] row_mask:0xf bank_mask:0xf
	ds_read_b128 v[88:91], v0 offset:50688
	ds_read_b128 v[92:95], v0 offset:50944
	v_add_f32_dpp v129, v129, v129 quad_perm:[2,3,0,1] row_mask:0xf bank_mask:0xf
	ds_read_b128 v[96:99], v0 offset:52224
	ds_read_b128 v[100:103], v0 offset:52480
	v_fmac_f32_dpp v104, -v129, v108 row_newbcast:0 row_mask:0xf bank_mask:0xf
	v_mul_f32_dpp v141, v129, v108 row_newbcast:4 row_mask:0xf bank_mask:0xf
	v_mul_f32_e32 v138, s29, v104
	v_mul_f32_dpp v139, v129, v108 row_newbcast:8 row_mask:0xf bank_mask:0xf
	v_fmac_f32_e32 v141, s31, v138
	v_mul_f32_dpp v143, v129, v108 row_newbcast:12 row_mask:0xf bank_mask:0xf
	v_fma_f32 v105, -s32, v141, v105
	v_mul_f32_e32 v144, s32, v138
	v_mul_f32_e32 v140, s33, v105
	v_fmac_f32_e32 v139, s30, v138
	v_pk_fma_f32 v[2:3], v[56:57], v[144:145], v[2:3] op_sel_hi:[1,0,1]
	v_fmac_f32_e32 v143, s35, v138
	v_pk_fma_f32 v[4:5], v[58:59], v[144:145], v[4:5] op_sel_hi:[1,0,1]
	v_pk_fma_f32 v[6:7], v[60:61], v[144:145], v[6:7] op_sel_hi:[1,0,1]
	v_pk_fma_f32 v[8:9], v[62:63], v[144:145], v[8:9] op_sel_hi:[1,0,1]
	v_pk_fma_f32 v[2:3], v[64:65], v[140:141], v[2:3] op_sel_hi:[1,0,1]
	v_pk_fma_f32 v[4:5], v[66:67], v[140:141], v[4:5] op_sel_hi:[1,0,1]
	v_pk_fma_f32 v[6:7], v[68:69], v[140:141], v[6:7] op_sel_hi:[1,0,1]
	v_pk_fma_f32 v[8:9], v[70:71], v[140:141], v[8:9] op_sel_hi:[1,0,1]
	s_waitcnt lgkmcnt(0)
	s_load_dwordx8 s[88:95], s[96:97], 0x20
	v_mov_b32_e32 v108, s4
	v_pk_mul_f32 v[124:125], v[2:3], v[72:73]
	v_mul_f32_e32 v143, s32, v143
	v_pk_mul_f32 v[126:127], v[2:3], v[88:89]
	v_fmac_f32_e32 v143, s34, v140
	v_pk_mul_f32 v[128:129], v[2:3], v[80:81]
	ds_write2_b32 v55, v139, v143 offset0:192 offset1:208
	v_pk_mul_f32 v[134:135], v[2:3], v[96:97]
	v_pk_fma_f32 v[124:125], v[4:5], v[74:75], v[124:125]
	v_pk_fma_f32 v[126:127], v[4:5], v[90:91], v[126:127]
	v_pk_fma_f32 v[128:129], v[4:5], v[82:83], v[128:129]
	v_pk_fma_f32 v[134:135], v[4:5], v[98:99], v[134:135]
	v_pk_fma_f32 v[124:125], v[6:7], v[76:77], v[124:125]
	v_pk_fma_f32 v[126:127], v[6:7], v[92:93], v[126:127]
	v_pk_fma_f32 v[128:129], v[6:7], v[84:85], v[128:129]
	v_pk_fma_f32 v[134:135], v[6:7], v[100:101], v[134:135]
	v_pk_fma_f32 v[124:125], v[8:9], v[78:79], v[124:125]
	v_pk_fma_f32 v[126:127], v[8:9], v[94:95], v[126:127]
	v_pk_fma_f32 v[128:129], v[8:9], v[86:87], v[128:129]
	v_pk_fma_f32 v[134:135], v[8:9], v[102:103], v[134:135]
	v_add_f32_e32 v124, v124, v125
	v_add_f32_e32 v126, v126, v127
	v_add_f32_e32 v128, v128, v129
	v_add_f32_e32 v134, v134, v135
	v_mul_f32_e32 v142, s8, v108
	v_add_f32_dpp v125, v124, v124 row_mirror row_mask:0xf bank_mask:0xf
	v_add_f32_dpp v125, v126, v126 row_mirror row_mask:0xf bank_mask:0xc
	v_add_f32_dpp v127, v128, v128 row_mirror row_mask:0xf bank_mask:0xf
	v_add_f32_dpp v127, v134, v134 row_mirror row_mask:0xf bank_mask:0xc
	v_add_f32_dpp v129, v125, v125 row_half_mirror row_mask:0xf bank_mask:0xf
	v_pk_mul_f32 v[2:3], v[2:3], v[142:143] op_sel_hi:[1,0]
	v_pk_mul_f32 v[4:5], v[4:5], v[142:143] op_sel_hi:[1,0]
	v_add_f32_dpp v129, v127, v127 row_half_mirror row_mask:0xf bank_mask:0xa
	v_pk_mul_f32 v[6:7], v[6:7], v[142:143] op_sel_hi:[1,0]
	v_pk_mul_f32 v[8:9], v[8:9], v[142:143] op_sel_hi:[1,0]
	v_add_f32_dpp v129, v129, v129 quad_perm:[1,0,3,2] row_mask:0xf bank_mask:0xf
	s_nop 1
	v_add_f32_dpp v129, v129, v129 quad_perm:[2,3,0,1] row_mask:0xf bank_mask:0xf
	s_nop 1
	v_fmac_f32_dpp v106, -v129, v108 row_newbcast:0 row_mask:0xf bank_mask:0xf
	v_mul_f32_dpp v141, v129, v108 row_newbcast:4 row_mask:0xf bank_mask:0xf
	v_mul_f32_e32 v138, s5, v106
	v_mul_f32_dpp v139, v129, v108 row_newbcast:8 row_mask:0xf bank_mask:0xf
	v_fmac_f32_e32 v141, s7, v138
	v_mul_f32_dpp v143, v129, v108 row_newbcast:12 row_mask:0xf bank_mask:0xf
	v_fma_f32 v107, -s8, v141, v107
	v_mul_f32_e32 v144, s8, v138
	v_mul_f32_e32 v140, s9, v107
	v_fmac_f32_e32 v139, s6, v138
	v_pk_fma_f32 v[2:3], v[72:73], v[144:145], v[2:3] op_sel_hi:[1,0,1]
	v_fmac_f32_e32 v143, s11, v138
	v_pk_fma_f32 v[4:5], v[74:75], v[144:145], v[4:5] op_sel_hi:[1,0,1]
	v_pk_fma_f32 v[6:7], v[76:77], v[144:145], v[6:7] op_sel_hi:[1,0,1]
	v_pk_fma_f32 v[8:9], v[78:79], v[144:145], v[8:9] op_sel_hi:[1,0,1]
	v_pk_fma_f32 v[2:3], v[80:81], v[140:141], v[2:3] op_sel_hi:[1,0,1]
	v_pk_fma_f32 v[4:5], v[82:83], v[140:141], v[4:5] op_sel_hi:[1,0,1]
	v_pk_fma_f32 v[6:7], v[84:85], v[140:141], v[6:7] op_sel_hi:[1,0,1]
	v_pk_fma_f32 v[8:9], v[86:87], v[140:141], v[8:9] op_sel_hi:[1,0,1]
	v_mul_f32_e32 v143, s8, v143
	v_fmac_f32_e32 v143, s10, v140
	ds_write2_b32 v55, v139, v143 offset0:224 offset1:240

.LBB0_853:
	s_add_i32 s41, s14, 1
	s_and_saveexec_b64 s[26:27], s[44:45]
	s_xor_b64 vcc, exec, s[26:27]
	s_cbranch_execz .LBB0_855
	s_and_b32 s26, s41, 1
	s_mul_i32 s27, s26, 0xc200
	s_add_i32 s27, s27, 0
	v_add_u32_e32 v0, s27, v155
	v_add_u32_e32 v158, s27, v156
	v_mov_b32_e32 v123, s27
	v_lshl_add_u32 v159, s26, 11, v154
	v_add_u32_e32 v166, 0x400, v159
	s_lshl_b32 s96, s41, 9
	s_add_u32 s96, s100, s96
	s_addc_u32 s97, s101, 0
	ds_read_b128 v[6:9], v0 offset:4096
	ds_read_b128 v[10:13], v0 offset:4352
	ds_read_b128 v[14:17], v0 offset:4608
	ds_read_b128 v[18:21], v0 offset:4864
	ds_read_b128 v[22:25], v0 offset:5120
	ds_read2st64_b32 v[62:63], v158 offset0:25 offset1:26
	ds_read_b128 v[30:33], v0 offset:5632
	ds_read_b128 v[38:41], v0 offset:6144
	ds_read_b128 v[26:29], v0 offset:5376
	ds_read_b128 v[34:37], v0 offset:5888
	s_waitcnt lgkmcnt(9)
	v_pk_mul_f32 v[82:83], v[138:139], v[6:7]
	s_load_dwordx8 s[28:35], s[96:97], 0x40
	s_waitcnt lgkmcnt(8)
	v_pk_mul_f32 v[84:85], v[138:139], v[10:11]
	ds_read_b128 v[42:45], v0 offset:8192
	s_waitcnt lgkmcnt(8)
	v_pk_mul_f32 v[86:87], v[138:139], v[14:15]
	ds_read_b128 v[46:49], v0 offset:8448
	s_waitcnt lgkmcnt(8)
	v_pk_mul_f32 v[88:89], v[138:139], v[18:19]
	ds_read_b128 v[50:53], v0 offset:8704
	v_pk_fma_f32 v[82:83], v[140:141], v[8:9], v[82:83]
	ds_read_b128 v[54:57], v0 offset:8960
	v_pk_fma_f32 v[84:85], v[140:141], v[12:13], v[84:85]
	ds_read_b128 v[58:61], v0 offset:9216
	v_pk_fma_f32 v[86:87], v[140:141], v[16:17], v[86:87]
	ds_read2st64_b32 v[72:73], v158 offset0:37 offset1:38
	v_pk_fma_f32 v[88:89], v[140:141], v[20:21], v[88:89]
	s_waitcnt lgkmcnt(11)
	v_pk_mul_f32 v[138:139], v[138:139], v[22:23]
	v_pk_mul_f32 v[140:141], v[140:141], v[24:25]
	v_add_f32_e32 v82, v82, v83
	v_add_f32_e32 v84, v84, v85
	v_add_f32_e32 v86, v86, v87
	v_add_f32_e32 v88, v88, v89
	ds_read_b128 v[6:9], v0 offset:7168
	ds_read_b128 v[10:13], v0 offset:7424
	ds_read_b128 v[14:17], v0 offset:7680
	ds_read_b128 v[18:21], v0 offset:7936
	v_add_f32_dpp v83, v82, v82 row_mirror row_mask:0xf bank_mask:0xf
	v_add_f32_dpp v83, v84, v84 row_mirror row_mask:0xf bank_mask:0xc
	v_add_f32_dpp v85, v86, v86 row_mirror row_mask:0xf bank_mask:0xf
	v_add_f32_dpp v85, v88, v88 row_mirror row_mask:0xf bank_mask:0xc
	v_add_f32_dpp v87, v83, v83 row_half_mirror row_mask:0xf bank_mask:0xf
	s_waitcnt lgkmcnt(13)
	v_pk_fma_f32 v[138:139], v[30:31], v[62:63], v[138:139] op_sel_hi:[1,0,1]
	v_pk_fma_f32 v[140:141], v[32:33], v[62:63], v[140:141] op_sel_hi:[1,0,1]
	v_add_f32_dpp v87, v85, v85 row_half_mirror row_mask:0xf bank_mask:0xa
	s_waitcnt lgkmcnt(12)
	v_pk_fma_f32 v[138:139], v[38:39], v[62:63], v[138:139] op_sel:[0,1,0] op_sel_hi:[1,1,1]
	v_pk_fma_f32 v[140:141], v[40:41], v[62:63], v[140:141] op_sel:[0,1,0] op_sel_hi:[1,1,1]
	v_add_f32_dpp v87, v87, v87 quad_perm:[1,0,3,2] row_mask:0xf bank_mask:0xf
	v_mul_f32_e32 v134, s77, v62
	v_mul_f32_e32 v135, s83, v62
	v_add_f32_dpp v87, v87, v87 quad_perm:[2,3,0,1] row_mask:0xf bank_mask:0xf
	v_fmac_f32_e32 v135, s81, v63
	v_mul_f32_e32 v92, s79, v62
	v_mov_b32_dpp v90, v87 row_newbcast:0 row_mask:0xf bank_mask:0xf
	v_add_f32_dpp v92, v87, v92 row_newbcast:4 row_mask:0xf bank_mask:0xf
	v_add_f32_dpp v91, v87, v134 row_newbcast:8 row_mask:0xf bank_mask:0xf
	s_waitcnt lgkmcnt(11)
	v_pk_fma_f32 v[138:139], v[26:27], v[90:91], v[138:139] op_sel_hi:[1,0,1] neg_lo:[0,1,0] neg_hi:[0,1,0]
	v_fma_f32 v92, -v90, s78, v92
	v_pk_fma_f32 v[140:141], v[28:29], v[90:91], v[140:141] op_sel_hi:[1,0,1] neg_lo:[0,1,0] neg_hi:[0,1,0]
	v_add_f32_dpp v93, v87, v135 row_newbcast:12 row_mask:0xf bank_mask:0xf
	s_waitcnt lgkmcnt(10)
	v_pk_fma_f32 v[138:139], v[34:35], v[92:93], v[138:139] op_sel_hi:[1,0,1] neg_lo:[0,1,0] neg_hi:[0,1,0]
	v_pk_fma_f32 v[140:141], v[36:37], v[92:93], v[140:141] op_sel_hi:[1,0,1] neg_lo:[0,1,0] neg_hi:[0,1,0]
	s_waitcnt lgkmcnt(0)
	s_load_dwordx8 s[4:11], s[96:97], 0x60
	v_pk_mul_f32 v[82:83], v[138:139], v[6:7]
	v_fma_f32 v91, -v90, s76, v91
	v_pk_mul_f32 v[84:85], v[138:139], v[10:11]
	v_fma_f32 v93, -v90, s82, v93
	v_pk_mul_f32 v[86:87], v[138:139], v[14:15]
	v_fma_f32 v93, -v92, s80, v93
	v_pk_mul_f32 v[88:89], v[138:139], v[18:19]
	ds_write2_b32 v159, v91, v93 offset0:0 offset1:16
	v_pk_fma_f32 v[82:83], v[140:141], v[8:9], v[82:83]
	ds_read_b128 v[22:25], v0 offset:11264
	v_pk_fma_f32 v[84:85], v[140:141], v[12:13], v[84:85]
	ds_read_b128 v[26:29], v0 offset:11520
	v_pk_fma_f32 v[86:87], v[140:141], v[16:17], v[86:87]
	ds_read_b128 v[30:33], v0 offset:11776
	v_pk_fma_f32 v[88:89], v[140:141], v[20:21], v[88:89]
	ds_read_b128 v[34:37], v0 offset:12032
	v_pk_mul_f32 v[138:139], v[138:139], v[42:43]
	ds_read_b128 v[38:41], v0 offset:12288
	v_pk_mul_f32 v[140:141], v[140:141], v[44:45]
	ds_read2st64_b32 v[62:63], v158 offset0:49 offset1:50
	v_add_f32_e32 v82, v82, v83
	v_add_f32_e32 v84, v84, v85
	v_add_f32_e32 v86, v86, v87
	v_add_f32_e32 v88, v88, v89
	ds_read_b128 v[6:9], v0 offset:10240
	ds_read_b128 v[10:13], v0 offset:10496
	ds_read_b128 v[14:17], v0 offset:10752
	ds_read_b128 v[18:21], v0 offset:11008
	v_add_f32_dpp v83, v82, v82 row_mirror row_mask:0xf bank_mask:0xf
	v_add_f32_dpp v83, v84, v84 row_mirror row_mask:0xf bank_mask:0xc
	v_add_f32_dpp v85, v86, v86 row_mirror row_mask:0xf bank_mask:0xf
	v_add_f32_dpp v85, v88, v88 row_mirror row_mask:0xf bank_mask:0xc
	v_add_f32_dpp v87, v83, v83 row_half_mirror row_mask:0xf bank_mask:0xf
	v_pk_fma_f32 v[138:139], v[50:51], v[72:73], v[138:139] op_sel_hi:[1,0,1]
	v_pk_fma_f32 v[140:141], v[52:53], v[72:73], v[140:141] op_sel_hi:[1,0,1]
	v_add_f32_dpp v87, v85, v85 row_half_mirror row_mask:0xf bank_mask:0xa
	v_pk_fma_f32 v[138:139], v[58:59], v[72:73], v[138:139] op_sel:[0,1,0] op_sel_hi:[1,1,1]
	v_pk_fma_f32 v[140:141], v[60:61], v[72:73], v[140:141] op_sel:[0,1,0] op_sel_hi:[1,1,1]
	v_add_f32_dpp v87, v87, v87 quad_perm:[1,0,3,2] row_mask:0xf bank_mask:0xf
	v_mul_f32_e32 v134, s89, v72
	v_mul_f32_e32 v135, s95, v72
	v_add_f32_dpp v87, v87, v87 quad_perm:[2,3,0,1] row_mask:0xf bank_mask:0xf
	v_fmac_f32_e32 v135, s93, v73
	v_mul_f32_e32 v92, s91, v72
	v_mov_b32_dpp v90, v87 row_newbcast:0 row_mask:0xf bank_mask:0xf
	v_add_f32_dpp v92, v87, v92 row_newbcast:4 row_mask:0xf bank_mask:0xf
	v_add_f32_dpp v91, v87, v134 row_newbcast:8 row_mask:0xf bank_mask:0xf
	v_pk_fma_f32 v[138:139], v[46:47], v[90:91], v[138:139] op_sel_hi:[1,0,1] neg_lo:[0,1,0] neg_hi:[0,1,0]
	v_fma_f32 v92, -v90, s90, v92
	v_pk_fma_f32 v[140:141], v[48:49], v[90:91], v[140:141] op_sel_hi:[1,0,1] neg_lo:[0,1,0] neg_hi:[0,1,0]
	v_add_f32_dpp v93, v87, v135 row_newbcast:12 row_mask:0xf bank_mask:0xf
	v_pk_fma_f32 v[138:139], v[54:55], v[92:93], v[138:139] op_sel_hi:[1,0,1] neg_lo:[0,1,0] neg_hi:[0,1,0]
	v_pk_fma_f32 v[140:141], v[56:57], v[92:93], v[140:141] op_sel_hi:[1,0,1] neg_lo:[0,1,0] neg_hi:[0,1,0]
	s_waitcnt lgkmcnt(0)
	s_load_dwordx8 s[76:83], s[96:97], 0x80
	v_pk_mul_f32 v[82:83], v[138:139], v[6:7]
	v_fma_f32 v91, -v90, s88, v91
	v_pk_mul_f32 v[84:85], v[138:139], v[10:11]
	v_fma_f32 v93, -v90, s94, v93
	v_pk_mul_f32 v[86:87], v[138:139], v[14:15]
	v_fma_f32 v93, -v92, s92, v93
	v_pk_mul_f32 v[88:89], v[138:139], v[18:19]
	ds_write2_b32 v159, v91, v93 offset0:32 offset1:48
	v_pk_fma_f32 v[82:83], v[140:141], v[8:9], v[82:83]
	ds_read_b128 v[42:45], v0 offset:14336
	v_pk_fma_f32 v[84:85], v[140:141], v[12:13], v[84:85]
	ds_read_b128 v[46:49], v0 offset:14592
	v_pk_fma_f32 v[86:87], v[140:141], v[16:17], v[86:87]
	ds_read_b128 v[50:53], v0 offset:14848
	v_pk_fma_f32 v[88:89], v[140:141], v[20:21], v[88:89]
	ds_read_b128 v[54:57], v0 offset:15104
	v_pk_mul_f32 v[138:139], v[138:139], v[22:23]
	ds_read_b128 v[58:61], v0 offset:15360
	v_pk_mul_f32 v[140:141], v[140:141], v[24:25]
	ds_read2st64_b32 v[72:73], v158 offset0:61 offset1:62
	v_add_f32_e32 v82, v82, v83
	v_add_f32_e32 v84, v84, v85
	v_add_f32_e32 v86, v86, v87
	v_add_f32_e32 v88, v88, v89
	ds_read_b128 v[6:9], v0 offset:13312
	ds_read_b128 v[10:13], v0 offset:13568
	ds_read_b128 v[14:17], v0 offset:13824
	ds_read_b128 v[18:21], v0 offset:14080
	v_add_f32_dpp v83, v82, v82 row_mirror row_mask:0xf bank_mask:0xf
	v_add_f32_dpp v83, v84, v84 row_mirror row_mask:0xf bank_mask:0xc
	v_add_f32_dpp v85, v86, v86 row_mirror row_mask:0xf bank_mask:0xf
	v_add_f32_dpp v85, v88, v88 row_mirror row_mask:0xf bank_mask:0xc
	v_add_f32_dpp v87, v83, v83 row_half_mirror row_mask:0xf bank_mask:0xf
	v_pk_fma_f32 v[138:139], v[30:31], v[62:63], v[138:139] op_sel_hi:[1,0,1]
	v_pk_fma_f32 v[140:141], v[32:33], v[62:63], v[140:141] op_sel_hi:[1,0,1]
	v_add_f32_dpp v87, v85, v85 row_half_mirror row_mask:0xf bank_mask:0xa
	v_pk_fma_f32 v[138:139], v[38:39], v[62:63], v[138:139] op_sel:[0,1,0] op_sel_hi:[1,1,1]
	v_pk_fma_f32 v[140:141], v[40:41], v[62:63], v[140:141] op_sel:[0,1,0] op_sel_hi:[1,1,1]
	v_add_f32_dpp v87, v87, v87 quad_perm:[1,0,3,2] row_mask:0xf bank_mask:0xf
	v_mul_f32_e32 v134, s29, v62
	v_mul_f32_e32 v135, s35, v62
	v_add_f32_dpp v87, v87, v87 quad_perm:[2,3,0,1] row_mask:0xf bank_mask:0xf
	v_fmac_f32_e32 v135, s33, v63
	v_mul_f32_e32 v92, s31, v62
	v_mov_b32_dpp v90, v87 row_newbcast:0 row_mask:0xf bank_mask:0xf
	v_add_f32_dpp v92, v87, v92 row_newbcast:4 row_mask:0xf bank_mask:0xf
	v_add_f32_dpp v91, v87, v134 row_newbcast:8 row_mask:0xf bank_mask:0xf
	v_pk_fma_f32 v[138:139], v[26:27], v[90:91], v[138:139] op_sel_hi:[1,0,1] neg_lo:[0,1,0] neg_hi:[0,1,0]
	v_fma_f32 v92, -v90, s30, v92
	v_pk_fma_f32 v[140:141], v[28:29], v[90:91], v[140:141] op_sel_hi:[1,0,1] neg_lo:[0,1,0] neg_hi:[0,1,0]
	v_add_f32_dpp v93, v87, v135 row_newbcast:12 row_mask:0xf bank_mask:0xf
	v_pk_fma_f32 v[138:139], v[34:35], v[92:93], v[138:139] op_sel_hi:[1,0,1] neg_lo:[0,1,0] neg_hi:[0,1,0]
	v_pk_fma_f32 v[140:141], v[36:37], v[92:93], v[140:141] op_sel_hi:[1,0,1] neg_lo:[0,1,0] neg_hi:[0,1,0]
	s_waitcnt lgkmcnt(0)
	s_load_dwordx8 s[88:95], s[96:97], 0xa0
	v_pk_mul_f32 v[82:83], v[138:139], v[6:7]
	v_fma_f32 v91, -v90, s28, v91
	v_pk_mul_f32 v[84:85], v[138:139], v[10:11]
	v_fma_f32 v93, -v90, s34, v93
	v_pk_mul_f32 v[86:87], v[138:139], v[14:15]
	v_fma_f32 v93, -v92, s32, v93
	v_pk_mul_f32 v[88:89], v[138:139], v[18:19]
	ds_write2_b32 v159, v91, v93 offset0:64 offset1:80
	v_pk_fma_f32 v[82:83], v[140:141], v[8:9], v[82:83]
	ds_read_b128 v[22:25], v0 offset:17408
	v_pk_fma_f32 v[84:85], v[140:141], v[12:13], v[84:85]
	ds_read_b128 v[26:29], v0 offset:17664
	v_pk_fma_f32 v[86:87], v[140:141], v[16:17], v[86:87]
	ds_read_b128 v[30:33], v0 offset:17920
	v_pk_fma_f32 v[88:89], v[140:141], v[20:21], v[88:89]
	ds_read_b128 v[34:37], v0 offset:18176
	v_pk_mul_f32 v[138:139], v[138:139], v[42:43]
	ds_read_b128 v[38:41], v0 offset:18432
	v_pk_mul_f32 v[140:141], v[140:141], v[44:45]
	ds_read2st64_b32 v[62:63], v158 offset0:73 offset1:74
	v_add_f32_e32 v82, v82, v83
	v_add_f32_e32 v84, v84, v85
	v_add_f32_e32 v86, v86, v87
	v_add_f32_e32 v88, v88, v89
	ds_read_b128 v[6:9], v0 offset:16384
	ds_read_b128 v[10:13], v0 offset:16640
	ds_read_b128 v[14:17], v0 offset:16896
	ds_read_b128 v[18:21], v0 offset:17152
	v_add_f32_dpp v83, v82, v82 row_mirror row_mask:0xf bank_mask:0xf
	v_add_f32_dpp v83, v84, v84 row_mirror row_mask:0xf bank_mask:0xc
	v_add_f32_dpp v85, v86, v86 row_mirror row_mask:0xf bank_mask:0xf
	v_add_f32_dpp v85, v88, v88 row_mirror row_mask:0xf bank_mask:0xc
	v_add_f32_dpp v87, v83, v83 row_half_mirror row_mask:0xf bank_mask:0xf
	v_pk_fma_f32 v[138:139], v[50:51], v[72:73], v[138:139] op_sel_hi:[1,0,1]
	v_pk_fma_f32 v[140:141], v[52:53], v[72:73], v[140:141] op_sel_hi:[1,0,1]
	v_add_f32_dpp v87, v85, v85 row_half_mirror row_mask:0xf bank_mask:0xa
	v_pk_fma_f32 v[138:139], v[58:59], v[72:73], v[138:139] op_sel:[0,1,0] op_sel_hi:[1,1,1]
	v_pk_fma_f32 v[140:141], v[60:61], v[72:73], v[140:141] op_sel:[0,1,0] op_sel_hi:[1,1,1]
	v_add_f32_dpp v87, v87, v87 quad_perm:[1,0,3,2] row_mask:0xf bank_mask:0xf
	v_mul_f32_e32 v134, s5, v72
	v_mul_f32_e32 v135, s11, v72
	v_add_f32_dpp v87, v87, v87 quad_perm:[2,3,0,1] row_mask:0xf bank_mask:0xf
	v_fmac_f32_e32 v135, s9, v73
	v_mul_f32_e32 v92, s7, v72
	v_mov_b32_dpp v90, v87 row_newbcast:0 row_mask:0xf bank_mask:0xf
	v_add_f32_dpp v92, v87, v92 row_newbcast:4 row_mask:0xf bank_mask:0xf
	v_add_f32_dpp v91, v87, v134 row_newbcast:8 row_mask:0xf bank_mask:0xf
	v_pk_fma_f32 v[138:139], v[46:47], v[90:91], v[138:139] op_sel_hi:[1,0,1] neg_lo:[0,1,0] neg_hi:[0,1,0]
	v_fma_f32 v92, -v90, s6, v92
	v_pk_fma_f32 v[140:141], v[48:49], v[90:91], v[140:141] op_sel_hi:[1,0,1] neg_lo:[0,1,0] neg_hi:[0,1,0]
	v_add_f32_dpp v93, v87, v135 row_newbcast:12 row_mask:0xf bank_mask:0xf
	v_pk_fma_f32 v[138:139], v[54:55], v[92:93], v[138:139] op_sel_hi:[1,0,1] neg_lo:[0,1,0] neg_hi:[0,1,0]
	v_pk_fma_f32 v[140:141], v[56:57], v[92:93], v[140:141] op_sel_hi:[1,0,1] neg_lo:[0,1,0] neg_hi:[0,1,0]
	s_waitcnt lgkmcnt(0)
	s_load_dwordx8 s[28:35], s[96:97], 0xc0
	v_pk_mul_f32 v[82:83], v[138:139], v[6:7]
	v_fma_f32 v91, -v90, s4, v91
	v_pk_mul_f32 v[84:85], v[138:139], v[10:11]
	v_fma_f32 v93, -v90, s10, v93
	v_pk_mul_f32 v[86:87], v[138:139], v[14:15]
	v_fma_f32 v93, -v92, s8, v93
	v_pk_mul_f32 v[88:89], v[138:139], v[18:19]
	ds_write2_b32 v159, v91, v93 offset0:96 offset1:112
	v_pk_fma_f32 v[82:83], v[140:141], v[8:9], v[82:83]
	ds_read_b128 v[42:45], v0 offset:20480
	v_pk_fma_f32 v[84:85], v[140:141], v[12:13], v[84:85]
	ds_read_b128 v[46:49], v0 offset:20736
	v_pk_fma_f32 v[86:87], v[140:141], v[16:17], v[86:87]
	ds_read_b128 v[50:53], v0 offset:20992
	v_pk_fma_f32 v[88:89], v[140:141], v[20:21], v[88:89]
	ds_read_b128 v[54:57], v0 offset:21248
	v_pk_mul_f32 v[138:139], v[138:139], v[22:23]
	ds_read_b128 v[58:61], v0 offset:21504
	v_pk_mul_f32 v[140:141], v[140:141], v[24:25]
	ds_read2st64_b32 v[72:73], v158 offset0:85 offset1:86
	v_add_f32_e32 v82, v82, v83
	v_add_f32_e32 v84, v84, v85
	v_add_f32_e32 v86, v86, v87
	v_add_f32_e32 v88, v88, v89
	ds_read_b128 v[6:9], v0 offset:19456
	ds_read_b128 v[10:13], v0 offset:19712
	ds_read_b128 v[14:17], v0 offset:19968
	ds_read_b128 v[18:21], v0 offset:20224
	v_add_f32_dpp v83, v82, v82 row_mirror row_mask:0xf bank_mask:0xf
	v_add_f32_dpp v83, v84, v84 row_mirror row_mask:0xf bank_mask:0xc
	v_add_f32_dpp v85, v86, v86 row_mirror row_mask:0xf bank_mask:0xf
	v_add_f32_dpp v85, v88, v88 row_mirror row_mask:0xf bank_mask:0xc
	v_add_f32_dpp v87, v83, v83 row_half_mirror row_mask:0xf bank_mask:0xf
	v_pk_fma_f32 v[138:139], v[30:31], v[62:63], v[138:139] op_sel_hi:[1,0,1]
	v_pk_fma_f32 v[140:141], v[32:33], v[62:63], v[140:141] op_sel_hi:[1,0,1]
	v_add_f32_dpp v87, v85, v85 row_half_mirror row_mask:0xf bank_mask:0xa
	v_pk_fma_f32 v[138:139], v[38:39], v[62:63], v[138:139] op_sel:[0,1,0] op_sel_hi:[1,1,1]
	v_pk_fma_f32 v[140:141], v[40:41], v[62:63], v[140:141] op_sel:[0,1,0] op_sel_hi:[1,1,1]
	v_add_f32_dpp v87, v87, v87 quad_perm:[1,0,3,2] row_mask:0xf bank_mask:0xf
	v_mul_f32_e32 v134, s77, v62
	v_mul_f32_e32 v135, s83, v62
	v_add_f32_dpp v87, v87, v87 quad_perm:[2,3,0,1] row_mask:0xf bank_mask:0xf
	v_fmac_f32_e32 v135, s81, v63
	v_mul_f32_e32 v92, s79, v62
	v_mov_b32_dpp v90, v87 row_newbcast:0 row_mask:0xf bank_mask:0xf
	v_add_f32_dpp v92, v87, v92 row_newbcast:4 row_mask:0xf bank_mask:0xf
	v_add_f32_dpp v91, v87, v134 row_newbcast:8 row_mask:0xf bank_mask:0xf
	v_pk_fma_f32 v[138:139], v[26:27], v[90:91], v[138:139] op_sel_hi:[1,0,1] neg_lo:[0,1,0] neg_hi:[0,1,0]
	v_fma_f32 v92, -v90, s78, v92
	v_pk_fma_f32 v[140:141], v[28:29], v[90:91], v[140:141] op_sel_hi:[1,0,1] neg_lo:[0,1,0] neg_hi:[0,1,0]
	v_add_f32_dpp v93, v87, v135 row_newbcast:12 row_mask:0xf bank_mask:0xf
	v_pk_fma_f32 v[138:139], v[34:35], v[92:93], v[138:139] op_sel_hi:[1,0,1] neg_lo:[0,1,0] neg_hi:[0,1,0]
	v_pk_fma_f32 v[140:141], v[36:37], v[92:93], v[140:141] op_sel_hi:[1,0,1] neg_lo:[0,1,0] neg_hi:[0,1,0]
	s_waitcnt lgkmcnt(0)
	s_load_dwordx8 s[4:11], s[96:97], 0xe0
	v_pk_mul_f32 v[82:83], v[138:139], v[6:7]
	v_fma_f32 v91, -v90, s76, v91
	v_pk_mul_f32 v[84:85], v[138:139], v[10:11]
	v_fma_f32 v93, -v90, s82, v93
	v_pk_mul_f32 v[86:87], v[138:139], v[14:15]
	v_fma_f32 v93, -v92, s80, v93
	v_pk_mul_f32 v[88:89], v[138:139], v[18:19]
	ds_write2_b32 v159, v91, v93 offset0:128 offset1:144
	v_pk_fma_f32 v[82:83], v[140:141], v[8:9], v[82:83]
	ds_read_b128 v[22:25], v0 offset:23552
	v_pk_fma_f32 v[84:85], v[140:141], v[12:13], v[84:85]
	ds_read_b128 v[26:29], v0 offset:23808
	v_pk_fma_f32 v[86:87], v[140:141], v[16:17], v[86:87]
	ds_read_b128 v[30:33], v0 offset:24064
	v_pk_fma_f32 v[88:89], v[140:141], v[20:21], v[88:89]
	ds_read_b128 v[34:37], v0 offset:24320
	v_pk_mul_f32 v[138:139], v[138:139], v[42:43]
	ds_read_b128 v[38:41], v0 offset:24576
	v_pk_mul_f32 v[140:141], v[140:141], v[44:45]
	ds_read2st64_b32 v[62:63], v158 offset0:97 offset1:98
	v_add_f32_e32 v82, v82, v83
	v_add_f32_e32 v84, v84, v85
	v_add_f32_e32 v86, v86, v87
	v_add_f32_e32 v88, v88, v89
	ds_read_b128 v[6:9], v0 offset:22528
	ds_read_b128 v[10:13], v0 offset:22784
	ds_read_b128 v[14:17], v0 offset:23040
	ds_read_b128 v[18:21], v0 offset:23296
	v_add_f32_dpp v83, v82, v82 row_mirror row_mask:0xf bank_mask:0xf
	v_add_f32_dpp v83, v84, v84 row_mirror row_mask:0xf bank_mask:0xc
	v_add_f32_dpp v85, v86, v86 row_mirror row_mask:0xf bank_mask:0xf
	v_add_f32_dpp v85, v88, v88 row_mirror row_mask:0xf bank_mask:0xc
	v_add_f32_dpp v87, v83, v83 row_half_mirror row_mask:0xf bank_mask:0xf
	v_pk_fma_f32 v[138:139], v[50:51], v[72:73], v[138:139] op_sel_hi:[1,0,1]
	v_pk_fma_f32 v[140:141], v[52:53], v[72:73], v[140:141] op_sel_hi:[1,0,1]
	v_add_f32_dpp v87, v85, v85 row_half_mirror row_mask:0xf bank_mask:0xa
	v_pk_fma_f32 v[138:139], v[58:59], v[72:73], v[138:139] op_sel:[0,1,0] op_sel_hi:[1,1,1]
	v_pk_fma_f32 v[140:141], v[60:61], v[72:73], v[140:141] op_sel:[0,1,0] op_sel_hi:[1,1,1]
	v_add_f32_dpp v87, v87, v87 quad_perm:[1,0,3,2] row_mask:0xf bank_mask:0xf
	v_mul_f32_e32 v134, s89, v72
	v_mul_f32_e32 v135, s95, v72
	v_add_f32_dpp v87, v87, v87 quad_perm:[2,3,0,1] row_mask:0xf bank_mask:0xf
	v_fmac_f32_e32 v135, s93, v73
	v_mul_f32_e32 v92, s91, v72
	v_mov_b32_dpp v90, v87 row_newbcast:0 row_mask:0xf bank_mask:0xf
	v_add_f32_dpp v92, v87, v92 row_newbcast:4 row_mask:0xf bank_mask:0xf
	v_add_f32_dpp v91, v87, v134 row_newbcast:8 row_mask:0xf bank_mask:0xf
	v_pk_fma_f32 v[138:139], v[46:47], v[90:91], v[138:139] op_sel_hi:[1,0,1] neg_lo:[0,1,0] neg_hi:[0,1,0]
	v_fma_f32 v92, -v90, s90, v92
	v_pk_fma_f32 v[140:141], v[48:49], v[90:91], v[140:141] op_sel_hi:[1,0,1] neg_lo:[0,1,0] neg_hi:[0,1,0]
	v_add_f32_dpp v93, v87, v135 row_newbcast:12 row_mask:0xf bank_mask:0xf
	v_pk_fma_f32 v[138:139], v[54:55], v[92:93], v[138:139] op_sel_hi:[1,0,1] neg_lo:[0,1,0] neg_hi:[0,1,0]
	v_pk_fma_f32 v[140:141], v[56:57], v[92:93], v[140:141] op_sel_hi:[1,0,1] neg_lo:[0,1,0] neg_hi:[0,1,0]
	s_waitcnt lgkmcnt(0)
	s_load_dwordx8 s[76:83], s[96:97], 0x100
	v_pk_mul_f32 v[82:83], v[138:139], v[6:7]
	v_fma_f32 v91, -v90, s88, v91
	v_pk_mul_f32 v[84:85], v[138:139], v[10:11]
	v_fma_f32 v93, -v90, s94, v93
	v_pk_mul_f32 v[86:87], v[138:139], v[14:15]
	v_fma_f32 v93, -v92, s92, v93
	v_pk_mul_f32 v[88:89], v[138:139], v[18:19]
	ds_write2_b32 v159, v91, v93 offset0:160 offset1:176
	v_pk_fma_f32 v[82:83], v[140:141], v[8:9], v[82:83]
	ds_read_b128 v[42:45], v0 offset:26624
	v_pk_fma_f32 v[84:85], v[140:141], v[12:13], v[84:85]
	ds_read_b128 v[46:49], v0 offset:26880
	v_pk_fma_f32 v[86:87], v[140:141], v[16:17], v[86:87]
	ds_read_b128 v[50:53], v0 offset:27136
	v_pk_fma_f32 v[88:89], v[140:141], v[20:21], v[88:89]
	ds_read_b128 v[54:57], v0 offset:27392
	v_pk_mul_f32 v[138:139], v[138:139], v[22:23]
	ds_read_b128 v[58:61], v0 offset:27648
	v_pk_mul_f32 v[140:141], v[140:141], v[24:25]
	ds_read2st64_b32 v[72:73], v158 offset0:109 offset1:110
	v_add_f32_e32 v82, v82, v83
	v_add_f32_e32 v84, v84, v85
	v_add_f32_e32 v86, v86, v87
	v_add_f32_e32 v88, v88, v89
	ds_read_b128 v[6:9], v0 offset:25600
	ds_read_b128 v[10:13], v0 offset:25856
	ds_read_b128 v[14:17], v0 offset:26112
	ds_read_b128 v[18:21], v0 offset:26368
	v_add_f32_dpp v83, v82, v82 row_mirror row_mask:0xf bank_mask:0xf
	v_add_f32_dpp v83, v84, v84 row_mirror row_mask:0xf bank_mask:0xc
	v_add_f32_dpp v85, v86, v86 row_mirror row_mask:0xf bank_mask:0xf
	v_add_f32_dpp v85, v88, v88 row_mirror row_mask:0xf bank_mask:0xc
	v_add_f32_dpp v87, v83, v83 row_half_mirror row_mask:0xf bank_mask:0xf
	v_pk_fma_f32 v[138:139], v[30:31], v[62:63], v[138:139] op_sel_hi:[1,0,1]
	v_pk_fma_f32 v[140:141], v[32:33], v[62:63], v[140:141] op_sel_hi:[1,0,1]
	v_add_f32_dpp v87, v85, v85 row_half_mirror row_mask:0xf bank_mask:0xa
	v_pk_fma_f32 v[138:139], v[38:39], v[62:63], v[138:139] op_sel:[0,1,0] op_sel_hi:[1,1,1]
	v_pk_fma_f32 v[140:141], v[40:41], v[62:63], v[140:141] op_sel:[0,1,0] op_sel_hi:[1,1,1]
	v_add_f32_dpp v87, v87, v87 quad_perm:[1,0,3,2] row_mask:0xf bank_mask:0xf
	v_mul_f32_e32 v134, s29, v62
	v_mul_f32_e32 v135, s35, v62
	v_add_f32_dpp v87, v87, v87 quad_perm:[2,3,0,1] row_mask:0xf bank_mask:0xf
	v_fmac_f32_e32 v135, s33, v63
	v_mul_f32_e32 v92, s31, v62
	v_mov_b32_dpp v90, v87 row_newbcast:0 row_mask:0xf bank_mask:0xf
	v_add_f32_dpp v92, v87, v92 row_newbcast:4 row_mask:0xf bank_mask:0xf
	v_add_f32_dpp v91, v87, v134 row_newbcast:8 row_mask:0xf bank_mask:0xf
	v_pk_fma_f32 v[138:139], v[26:27], v[90:91], v[138:139] op_sel_hi:[1,0,1] neg_lo:[0,1,0] neg_hi:[0,1,0]
	v_fma_f32 v92, -v90, s30, v92
	v_pk_fma_f32 v[140:141], v[28:29], v[90:91], v[140:141] op_sel_hi:[1,0,1] neg_lo:[0,1,0] neg_hi:[0,1,0]
	v_add_f32_dpp v93, v87, v135 row_newbcast:12 row_mask:0xf bank_mask:0xf
	v_pk_fma_f32 v[138:139], v[34:35], v[92:93], v[138:139] op_sel_hi:[1,0,1] neg_lo:[0,1,0] neg_hi:[0,1,0]
	v_pk_fma_f32 v[140:141], v[36:37], v[92:93], v[140:141] op_sel_hi:[1,0,1] neg_lo:[0,1,0] neg_hi:[0,1,0]
	s_waitcnt lgkmcnt(0)
	s_load_dwordx8 s[88:95], s[96:97], 0x120
	v_pk_mul_f32 v[82:83], v[138:139], v[6:7]
	v_fma_f32 v91, -v90, s28, v91
	v_pk_mul_f32 v[84:85], v[138:139], v[10:11]
	v_fma_f32 v93, -v90, s34, v93
	v_pk_mul_f32 v[86:87], v[138:139], v[14:15]
	v_fma_f32 v93, -v92, s32, v93
	v_pk_mul_f32 v[88:89], v[138:139], v[18:19]
	ds_write2_b32 v159, v91, v93 offset0:192 offset1:208
	v_pk_fma_f32 v[82:83], v[140:141], v[8:9], v[82:83]
	ds_read_b128 v[22:25], v0 offset:29696
	v_pk_fma_f32 v[84:85], v[140:141], v[12:13], v[84:85]
	ds_read_b128 v[26:29], v0 offset:29952
	v_pk_fma_f32 v[86:87], v[140:141], v[16:17], v[86:87]
	ds_read_b128 v[30:33], v0 offset:30208
	v_pk_fma_f32 v[88:89], v[140:141], v[20:21], v[88:89]
	ds_read_b128 v[34:37], v0 offset:30464
	v_pk_mul_f32 v[138:139], v[138:139], v[42:43]
	ds_read_b128 v[38:41], v0 offset:30720
	v_pk_mul_f32 v[140:141], v[140:141], v[44:45]
	ds_read2st64_b32 v[62:63], v158 offset0:121 offset1:122
	v_add_f32_e32 v82, v82, v83
	v_add_f32_e32 v84, v84, v85
	v_add_f32_e32 v86, v86, v87
	v_add_f32_e32 v88, v88, v89
	ds_read_b128 v[6:9], v0 offset:28672
	ds_read_b128 v[10:13], v0 offset:28928
	ds_read_b128 v[14:17], v0 offset:29184
	ds_read_b128 v[18:21], v0 offset:29440
	v_add_f32_dpp v83, v82, v82 row_mirror row_mask:0xf bank_mask:0xf
	v_add_f32_dpp v83, v84, v84 row_mirror row_mask:0xf bank_mask:0xc
	v_add_f32_dpp v85, v86, v86 row_mirror row_mask:0xf bank_mask:0xf
	v_add_f32_dpp v85, v88, v88 row_mirror row_mask:0xf bank_mask:0xc
	v_add_f32_dpp v87, v83, v83 row_half_mirror row_mask:0xf bank_mask:0xf
	v_pk_fma_f32 v[138:139], v[50:51], v[72:73], v[138:139] op_sel_hi:[1,0,1]
	v_pk_fma_f32 v[140:141], v[52:53], v[72:73], v[140:141] op_sel_hi:[1,0,1]
	v_add_f32_dpp v87, v85, v85 row_half_mirror row_mask:0xf bank_mask:0xa
	v_pk_fma_f32 v[138:139], v[58:59], v[72:73], v[138:139] op_sel:[0,1,0] op_sel_hi:[1,1,1]
	v_pk_fma_f32 v[140:141], v[60:61], v[72:73], v[140:141] op_sel:[0,1,0] op_sel_hi:[1,1,1]
	v_add_f32_dpp v87, v87, v87 quad_perm:[1,0,3,2] row_mask:0xf bank_mask:0xf
	v_mul_f32_e32 v134, s5, v72
	v_mul_f32_e32 v135, s11, v72
	v_add_f32_dpp v87, v87, v87 quad_perm:[2,3,0,1] row_mask:0xf bank_mask:0xf
	v_fmac_f32_e32 v135, s9, v73
	v_mul_f32_e32 v92, s7, v72
	v_mov_b32_dpp v90, v87 row_newbcast:0 row_mask:0xf bank_mask:0xf
	v_add_f32_dpp v92, v87, v92 row_newbcast:4 row_mask:0xf bank_mask:0xf
	v_add_f32_dpp v91, v87, v134 row_newbcast:8 row_mask:0xf bank_mask:0xf
	v_pk_fma_f32 v[138:139], v[46:47], v[90:91], v[138:139] op_sel_hi:[1,0,1] neg_lo:[0,1,0] neg_hi:[0,1,0]
	v_fma_f32 v92, -v90, s6, v92
	v_pk_fma_f32 v[140:141], v[48:49], v[90:91], v[140:141] op_sel_hi:[1,0,1] neg_lo:[0,1,0] neg_hi:[0,1,0]
	v_add_f32_dpp v93, v87, v135 row_newbcast:12 row_mask:0xf bank_mask:0xf
	v_pk_fma_f32 v[138:139], v[54:55], v[92:93], v[138:139] op_sel_hi:[1,0,1] neg_lo:[0,1,0] neg_hi:[0,1,0]
	v_pk_fma_f32 v[140:141], v[56:57], v[92:93], v[140:141] op_sel_hi:[1,0,1] neg_lo:[0,1,0] neg_hi:[0,1,0]
	s_waitcnt lgkmcnt(0)
	s_load_dwordx8 s[28:35], s[96:97], 0x140
	v_pk_mul_f32 v[82:83], v[138:139], v[6:7]
	v_fma_f32 v91, -v90, s4, v91
	v_pk_mul_f32 v[84:85], v[138:139], v[10:11]
	v_fma_f32 v93, -v90, s10, v93
	v_pk_mul_f32 v[86:87], v[138:139], v[14:15]
	v_fma_f32 v93, -v92, s8, v93
	v_pk_mul_f32 v[88:89], v[138:139], v[18:19]
	ds_write2_b32 v159, v91, v93 offset0:224 offset1:240
	v_pk_fma_f32 v[82:83], v[140:141], v[8:9], v[82:83]
	ds_read_b128 v[42:45], v0 offset:32768
	v_pk_fma_f32 v[84:85], v[140:141], v[12:13], v[84:85]
	ds_read_b128 v[46:49], v0 offset:33024
	v_pk_fma_f32 v[86:87], v[140:141], v[16:17], v[86:87]
	ds_read_b128 v[50:53], v0 offset:33280
	v_pk_fma_f32 v[88:89], v[140:141], v[20:21], v[88:89]
	ds_read_b128 v[54:57], v0 offset:33536
	v_pk_mul_f32 v[138:139], v[138:139], v[22:23]
	ds_read_b128 v[58:61], v0 offset:33792
	v_pk_mul_f32 v[140:141], v[140:141], v[24:25]
	ds_read2st64_b32 v[72:73], v158 offset0:133 offset1:134
	v_add_f32_e32 v82, v82, v83
	v_add_f32_e32 v84, v84, v85
	v_add_f32_e32 v86, v86, v87
	v_add_f32_e32 v88, v88, v89
	ds_read_b128 v[6:9], v0 offset:31744
	ds_read_b128 v[10:13], v0 offset:32000
	ds_read_b128 v[14:17], v0 offset:32256
	ds_read_b128 v[18:21], v0 offset:32512
	v_add_f32_dpp v83, v82, v82 row_mirror row_mask:0xf bank_mask:0xf
	v_add_f32_dpp v83, v84, v84 row_mirror row_mask:0xf bank_mask:0xc
	v_add_f32_dpp v85, v86, v86 row_mirror row_mask:0xf bank_mask:0xf
	v_add_f32_dpp v85, v88, v88 row_mirror row_mask:0xf bank_mask:0xc
	v_add_f32_dpp v87, v83, v83 row_half_mirror row_mask:0xf bank_mask:0xf
	v_pk_fma_f32 v[138:139], v[30:31], v[62:63], v[138:139] op_sel_hi:[1,0,1]
	v_pk_fma_f32 v[140:141], v[32:33], v[62:63], v[140:141] op_sel_hi:[1,0,1]
	v_add_f32_dpp v87, v85, v85 row_half_mirror row_mask:0xf bank_mask:0xa
	v_pk_fma_f32 v[138:139], v[38:39], v[62:63], v[138:139] op_sel:[0,1,0] op_sel_hi:[1,1,1]
	v_pk_fma_f32 v[140:141], v[40:41], v[62:63], v[140:141] op_sel:[0,1,0] op_sel_hi:[1,1,1]
	v_add_f32_dpp v87, v87, v87 quad_perm:[1,0,3,2] row_mask:0xf bank_mask:0xf
	v_mul_f32_e32 v134, s77, v62
	v_mul_f32_e32 v135, s83, v62
	v_add_f32_dpp v87, v87, v87 quad_perm:[2,3,0,1] row_mask:0xf bank_mask:0xf
	v_fmac_f32_e32 v135, s81, v63
	v_mul_f32_e32 v92, s79, v62
	v_mov_b32_dpp v90, v87 row_newbcast:0 row_mask:0xf bank_mask:0xf
	v_add_f32_dpp v92, v87, v92 row_newbcast:4 row_mask:0xf bank_mask:0xf
	v_add_f32_dpp v91, v87, v134 row_newbcast:8 row_mask:0xf bank_mask:0xf
	v_pk_fma_f32 v[138:139], v[26:27], v[90:91], v[138:139] op_sel_hi:[1,0,1] neg_lo:[0,1,0] neg_hi:[0,1,0]
	v_fma_f32 v92, -v90, s78, v92
	v_pk_fma_f32 v[140:141], v[28:29], v[90:91], v[140:141] op_sel_hi:[1,0,1] neg_lo:[0,1,0] neg_hi:[0,1,0]
	v_add_f32_dpp v93, v87, v135 row_newbcast:12 row_mask:0xf bank_mask:0xf
	v_pk_fma_f32 v[138:139], v[34:35], v[92:93], v[138:139] op_sel_hi:[1,0,1] neg_lo:[0,1,0] neg_hi:[0,1,0]
	v_pk_fma_f32 v[140:141], v[36:37], v[92:93], v[140:141] op_sel_hi:[1,0,1] neg_lo:[0,1,0] neg_hi:[0,1,0]
	s_waitcnt lgkmcnt(0)
	s_load_dwordx8 s[4:11], s[96:97], 0x160
	v_pk_mul_f32 v[82:83], v[138:139], v[6:7]
	v_fma_f32 v91, -v90, s76, v91
	v_pk_mul_f32 v[84:85], v[138:139], v[10:11]
	v_fma_f32 v93, -v90, s82, v93
	v_pk_mul_f32 v[86:87], v[138:139], v[14:15]
	v_fma_f32 v93, -v92, s80, v93
	v_pk_mul_f32 v[88:89], v[138:139], v[18:19]
	ds_write2_b32 v166, v91, v93 offset0:0 offset1:16
	v_pk_fma_f32 v[82:83], v[140:141], v[8:9], v[82:83]
	ds_read_b128 v[22:25], v0 offset:35840
	v_pk_fma_f32 v[84:85], v[140:141], v[12:13], v[84:85]
	ds_read_b128 v[26:29], v0 offset:36096
	v_pk_fma_f32 v[86:87], v[140:141], v[16:17], v[86:87]
	ds_read_b128 v[30:33], v0 offset:36352
	v_pk_fma_f32 v[88:89], v[140:141], v[20:21], v[88:89]
	ds_read_b128 v[34:37], v0 offset:36608
	v_pk_mul_f32 v[138:139], v[138:139], v[42:43]
	ds_read_b128 v[38:41], v0 offset:36864
	v_pk_mul_f32 v[140:141], v[140:141], v[44:45]
	ds_read2st64_b32 v[62:63], v158 offset0:145 offset1:146
	v_add_f32_e32 v82, v82, v83
	v_add_f32_e32 v84, v84, v85
	v_add_f32_e32 v86, v86, v87
	v_add_f32_e32 v88, v88, v89
	ds_read_b128 v[6:9], v0 offset:34816
	ds_read_b128 v[10:13], v0 offset:35072
	ds_read_b128 v[14:17], v0 offset:35328
	ds_read_b128 v[18:21], v0 offset:35584
	v_add_f32_dpp v83, v82, v82 row_mirror row_mask:0xf bank_mask:0xf
	v_add_f32_dpp v83, v84, v84 row_mirror row_mask:0xf bank_mask:0xc
	v_add_f32_dpp v85, v86, v86 row_mirror row_mask:0xf bank_mask:0xf
	v_add_f32_dpp v85, v88, v88 row_mirror row_mask:0xf bank_mask:0xc
	v_add_f32_dpp v87, v83, v83 row_half_mirror row_mask:0xf bank_mask:0xf
	v_pk_fma_f32 v[138:139], v[50:51], v[72:73], v[138:139] op_sel_hi:[1,0,1]
	v_pk_fma_f32 v[140:141], v[52:53], v[72:73], v[140:141] op_sel_hi:[1,0,1]
	v_add_f32_dpp v87, v85, v85 row_half_mirror row_mask:0xf bank_mask:0xa
	v_pk_fma_f32 v[138:139], v[58:59], v[72:73], v[138:139] op_sel:[0,1,0] op_sel_hi:[1,1,1]
	v_pk_fma_f32 v[140:141], v[60:61], v[72:73], v[140:141] op_sel:[0,1,0] op_sel_hi:[1,1,1]
	v_add_f32_dpp v87, v87, v87 quad_perm:[1,0,3,2] row_mask:0xf bank_mask:0xf
	v_mul_f32_e32 v134, s89, v72
	v_mul_f32_e32 v135, s95, v72
	v_add_f32_dpp v87, v87, v87 quad_perm:[2,3,0,1] row_mask:0xf bank_mask:0xf
	v_fmac_f32_e32 v135, s93, v73
	v_mul_f32_e32 v92, s91, v72
	v_mov_b32_dpp v90, v87 row_newbcast:0 row_mask:0xf bank_mask:0xf
	v_add_f32_dpp v92, v87, v92 row_newbcast:4 row_mask:0xf bank_mask:0xf
	v_add_f32_dpp v91, v87, v134 row_newbcast:8 row_mask:0xf bank_mask:0xf
	v_pk_fma_f32 v[138:139], v[46:47], v[90:91], v[138:139] op_sel_hi:[1,0,1] neg_lo:[0,1,0] neg_hi:[0,1,0]
	v_fma_f32 v92, -v90, s90, v92
	v_pk_fma_f32 v[140:141], v[48:49], v[90:91], v[140:141] op_sel_hi:[1,0,1] neg_lo:[0,1,0] neg_hi:[0,1,0]
	v_add_f32_dpp v93, v87, v135 row_newbcast:12 row_mask:0xf bank_mask:0xf
	v_pk_fma_f32 v[138:139], v[54:55], v[92:93], v[138:139] op_sel_hi:[1,0,1] neg_lo:[0,1,0] neg_hi:[0,1,0]
	v_pk_fma_f32 v[140:141], v[56:57], v[92:93], v[140:141] op_sel_hi:[1,0,1] neg_lo:[0,1,0] neg_hi:[0,1,0]
	s_waitcnt lgkmcnt(0)
	s_load_dwordx8 s[76:83], s[96:97], 0x180
	v_pk_mul_f32 v[82:83], v[138:139], v[6:7]
	v_fma_f32 v91, -v90, s88, v91
	v_pk_mul_f32 v[84:85], v[138:139], v[10:11]
	v_fma_f32 v93, -v90, s94, v93
	v_pk_mul_f32 v[86:87], v[138:139], v[14:15]
	v_fma_f32 v93, -v92, s92, v93
	v_pk_mul_f32 v[88:89], v[138:139], v[18:19]
	ds_write2_b32 v166, v91, v93 offset0:32 offset1:48
	v_pk_fma_f32 v[82:83], v[140:141], v[8:9], v[82:83]
	ds_read_b128 v[42:45], v0 offset:38912
	v_pk_fma_f32 v[84:85], v[140:141], v[12:13], v[84:85]
	ds_read_b128 v[46:49], v0 offset:39168
	v_pk_fma_f32 v[86:87], v[140:141], v[16:17], v[86:87]
	ds_read_b128 v[50:53], v0 offset:39424
	v_pk_fma_f32 v[88:89], v[140:141], v[20:21], v[88:89]
	ds_read_b128 v[54:57], v0 offset:39680
	v_pk_mul_f32 v[138:139], v[138:139], v[22:23]
	ds_read_b128 v[58:61], v0 offset:39936
	v_pk_mul_f32 v[140:141], v[140:141], v[24:25]
	ds_read2st64_b32 v[72:73], v158 offset0:157 offset1:158
	v_add_f32_e32 v82, v82, v83
	v_add_f32_e32 v84, v84, v85
	v_add_f32_e32 v86, v86, v87
	v_add_f32_e32 v88, v88, v89
	ds_read_b128 v[6:9], v0 offset:37888
	ds_read_b128 v[10:13], v0 offset:38144
	ds_read_b128 v[14:17], v0 offset:38400
	ds_read_b128 v[18:21], v0 offset:38656
	v_add_f32_dpp v83, v82, v82 row_mirror row_mask:0xf bank_mask:0xf
	v_add_f32_dpp v83, v84, v84 row_mirror row_mask:0xf bank_mask:0xc
	v_add_f32_dpp v85, v86, v86 row_mirror row_mask:0xf bank_mask:0xf
	v_add_f32_dpp v85, v88, v88 row_mirror row_mask:0xf bank_mask:0xc
	v_add_f32_dpp v87, v83, v83 row_half_mirror row_mask:0xf bank_mask:0xf
	v_pk_fma_f32 v[138:139], v[30:31], v[62:63], v[138:139] op_sel_hi:[1,0,1]
	v_pk_fma_f32 v[140:141], v[32:33], v[62:63], v[140:141] op_sel_hi:[1,0,1]
	v_add_f32_dpp v87, v85, v85 row_half_mirror row_mask:0xf bank_mask:0xa
	v_pk_fma_f32 v[138:139], v[38:39], v[62:63], v[138:139] op_sel:[0,1,0] op_sel_hi:[1,1,1]
	v_pk_fma_f32 v[140:141], v[40:41], v[62:63], v[140:141] op_sel:[0,1,0] op_sel_hi:[1,1,1]
	v_add_f32_dpp v87, v87, v87 quad_perm:[1,0,3,2] row_mask:0xf bank_mask:0xf
	v_mul_f32_e32 v134, s29, v62
	v_mul_f32_e32 v135, s35, v62
	v_add_f32_dpp v87, v87, v87 quad_perm:[2,3,0,1] row_mask:0xf bank_mask:0xf
	v_fmac_f32_e32 v135, s33, v63
	v_mul_f32_e32 v92, s31, v62
	v_mov_b32_dpp v90, v87 row_newbcast:0 row_mask:0xf bank_mask:0xf
	v_add_f32_dpp v92, v87, v92 row_newbcast:4 row_mask:0xf bank_mask:0xf
	v_add_f32_dpp v91, v87, v134 row_newbcast:8 row_mask:0xf bank_mask:0xf
	v_pk_fma_f32 v[138:139], v[26:27], v[90:91], v[138:139] op_sel_hi:[1,0,1] neg_lo:[0,1,0] neg_hi:[0,1,0]
	v_fma_f32 v92, -v90, s30, v92
	v_pk_fma_f32 v[140:141], v[28:29], v[90:91], v[140:141] op_sel_hi:[1,0,1] neg_lo:[0,1,0] neg_hi:[0,1,0]
	v_add_f32_dpp v93, v87, v135 row_newbcast:12 row_mask:0xf bank_mask:0xf
	v_pk_fma_f32 v[138:139], v[34:35], v[92:93], v[138:139] op_sel_hi:[1,0,1] neg_lo:[0,1,0] neg_hi:[0,1,0]
	v_pk_fma_f32 v[140:141], v[36:37], v[92:93], v[140:141] op_sel_hi:[1,0,1] neg_lo:[0,1,0] neg_hi:[0,1,0]
	s_waitcnt lgkmcnt(0)
	s_load_dwordx8 s[88:95], s[96:97], 0x1a0
	v_pk_mul_f32 v[82:83], v[138:139], v[6:7]
	v_fma_f32 v91, -v90, s28, v91
	v_pk_mul_f32 v[84:85], v[138:139], v[10:11]
	v_fma_f32 v93, -v90, s34, v93
	v_pk_mul_f32 v[86:87], v[138:139], v[14:15]
	v_fma_f32 v93, -v92, s32, v93
	v_pk_mul_f32 v[88:89], v[138:139], v[18:19]
	ds_write2_b32 v166, v91, v93 offset0:64 offset1:80
	v_pk_fma_f32 v[82:83], v[140:141], v[8:9], v[82:83]
	ds_read_b128 v[22:25], v0 offset:41984
	v_pk_fma_f32 v[84:85], v[140:141], v[12:13], v[84:85]
	ds_read_b128 v[26:29], v0 offset:42240
	v_pk_fma_f32 v[86:87], v[140:141], v[16:17], v[86:87]
	ds_read_b128 v[30:33], v0 offset:42496
	v_pk_fma_f32 v[88:89], v[140:141], v[20:21], v[88:89]
	ds_read_b128 v[34:37], v0 offset:42752
	v_pk_mul_f32 v[138:139], v[138:139], v[42:43]
	ds_read_b128 v[38:41], v0 offset:43008
	v_pk_mul_f32 v[140:141], v[140:141], v[44:45]
	ds_read2st64_b32 v[62:63], v158 offset0:169 offset1:170
	v_add_f32_e32 v82, v82, v83
	v_add_f32_e32 v84, v84, v85
	v_add_f32_e32 v86, v86, v87
	v_add_f32_e32 v88, v88, v89
	ds_read_b128 v[6:9], v0 offset:40960
	ds_read_b128 v[10:13], v0 offset:41216
	ds_read_b128 v[14:17], v0 offset:41472
	ds_read_b128 v[18:21], v0 offset:41728
	v_add_f32_dpp v83, v82, v82 row_mirror row_mask:0xf bank_mask:0xf
	v_add_f32_dpp v83, v84, v84 row_mirror row_mask:0xf bank_mask:0xc
	v_add_f32_dpp v85, v86, v86 row_mirror row_mask:0xf bank_mask:0xf
	v_add_f32_dpp v85, v88, v88 row_mirror row_mask:0xf bank_mask:0xc
	v_add_f32_dpp v87, v83, v83 row_half_mirror row_mask:0xf bank_mask:0xf
	v_pk_fma_f32 v[138:139], v[50:51], v[72:73], v[138:139] op_sel_hi:[1,0,1]
	v_pk_fma_f32 v[140:141], v[52:53], v[72:73], v[140:141] op_sel_hi:[1,0,1]
	v_add_f32_dpp v87, v85, v85 row_half_mirror row_mask:0xf bank_mask:0xa
	v_pk_fma_f32 v[138:139], v[58:59], v[72:73], v[138:139] op_sel:[0,1,0] op_sel_hi:[1,1,1]
	v_pk_fma_f32 v[140:141], v[60:61], v[72:73], v[140:141] op_sel:[0,1,0] op_sel_hi:[1,1,1]
	v_add_f32_dpp v87, v87, v87 quad_perm:[1,0,3,2] row_mask:0xf bank_mask:0xf
	v_mul_f32_e32 v134, s5, v72
	v_mul_f32_e32 v135, s11, v72
	v_add_f32_dpp v87, v87, v87 quad_perm:[2,3,0,1] row_mask:0xf bank_mask:0xf
	v_fmac_f32_e32 v135, s9, v73
	v_mul_f32_e32 v92, s7, v72
	v_mov_b32_dpp v90, v87 row_newbcast:0 row_mask:0xf bank_mask:0xf
	v_add_f32_dpp v92, v87, v92 row_newbcast:4 row_mask:0xf bank_mask:0xf
	v_add_f32_dpp v91, v87, v134 row_newbcast:8 row_mask:0xf bank_mask:0xf
	v_pk_fma_f32 v[138:139], v[46:47], v[90:91], v[138:139] op_sel_hi:[1,0,1] neg_lo:[0,1,0] neg_hi:[0,1,0]
	v_fma_f32 v92, -v90, s6, v92
	v_pk_fma_f32 v[140:141], v[48:49], v[90:91], v[140:141] op_sel_hi:[1,0,1] neg_lo:[0,1,0] neg_hi:[0,1,0]
	v_add_f32_dpp v93, v87, v135 row_newbcast:12 row_mask:0xf bank_mask:0xf
	v_pk_fma_f32 v[138:139], v[54:55], v[92:93], v[138:139] op_sel_hi:[1,0,1] neg_lo:[0,1,0] neg_hi:[0,1,0]
	v_pk_fma_f32 v[140:141], v[56:57], v[92:93], v[140:141] op_sel_hi:[1,0,1] neg_lo:[0,1,0] neg_hi:[0,1,0]
	s_waitcnt lgkmcnt(0)
	s_load_dwordx8 s[28:35], s[96:97], 0x1c0
	v_pk_mul_f32 v[82:83], v[138:139], v[6:7]
	v_fma_f32 v91, -v90, s4, v91
	v_pk_mul_f32 v[84:85], v[138:139], v[10:11]
	v_fma_f32 v93, -v90, s10, v93
	v_pk_mul_f32 v[86:87], v[138:139], v[14:15]
	v_fma_f32 v93, -v92, s8, v93
	v_pk_mul_f32 v[88:89], v[138:139], v[18:19]
	ds_write2_b32 v166, v91, v93 offset0:96 offset1:112
	v_pk_fma_f32 v[82:83], v[140:141], v[8:9], v[82:83]
	ds_read_b128 v[42:45], v0 offset:45056
	v_pk_fma_f32 v[84:85], v[140:141], v[12:13], v[84:85]
	ds_read_b128 v[46:49], v0 offset:45312
	v_pk_fma_f32 v[86:87], v[140:141], v[16:17], v[86:87]
	ds_read_b128 v[50:53], v0 offset:45568
	v_pk_fma_f32 v[88:89], v[140:141], v[20:21], v[88:89]
	ds_read_b128 v[54:57], v0 offset:45824
	v_pk_mul_f32 v[138:139], v[138:139], v[22:23]
	ds_read_b128 v[58:61], v0 offset:46080
	v_pk_mul_f32 v[140:141], v[140:141], v[24:25]
	ds_read2st64_b32 v[72:73], v158 offset0:181 offset1:182
	v_add_f32_e32 v82, v82, v83
	v_add_f32_e32 v84, v84, v85
	v_add_f32_e32 v86, v86, v87
	v_add_f32_e32 v88, v88, v89
	ds_read_b128 v[6:9], v0 offset:44032
	ds_read_b128 v[10:13], v0 offset:44288
	ds_read_b128 v[14:17], v0 offset:44544
	ds_read_b128 v[18:21], v0 offset:44800
	v_add_f32_dpp v83, v82, v82 row_mirror row_mask:0xf bank_mask:0xf
	v_add_f32_dpp v83, v84, v84 row_mirror row_mask:0xf bank_mask:0xc
	v_add_f32_dpp v85, v86, v86 row_mirror row_mask:0xf bank_mask:0xf
	v_add_f32_dpp v85, v88, v88 row_mirror row_mask:0xf bank_mask:0xc
	v_add_f32_dpp v87, v83, v83 row_half_mirror row_mask:0xf bank_mask:0xf
	v_pk_fma_f32 v[138:139], v[30:31], v[62:63], v[138:139] op_sel_hi:[1,0,1]
	v_pk_fma_f32 v[140:141], v[32:33], v[62:63], v[140:141] op_sel_hi:[1,0,1]
	v_add_f32_dpp v87, v85, v85 row_half_mirror row_mask:0xf bank_mask:0xa
	v_pk_fma_f32 v[138:139], v[38:39], v[62:63], v[138:139] op_sel:[0,1,0] op_sel_hi:[1,1,1]
	v_pk_fma_f32 v[140:141], v[40:41], v[62:63], v[140:141] op_sel:[0,1,0] op_sel_hi:[1,1,1]
	v_add_f32_dpp v87, v87, v87 quad_perm:[1,0,3,2] row_mask:0xf bank_mask:0xf
	v_mul_f32_e32 v134, s77, v62
	v_mul_f32_e32 v135, s83, v62
	v_add_f32_dpp v87, v87, v87 quad_perm:[2,3,0,1] row_mask:0xf bank_mask:0xf
	v_fmac_f32_e32 v135, s81, v63
	v_mul_f32_e32 v92, s79, v62
	v_mov_b32_dpp v90, v87 row_newbcast:0 row_mask:0xf bank_mask:0xf
	v_add_f32_dpp v92, v87, v92 row_newbcast:4 row_mask:0xf bank_mask:0xf
	v_add_f32_dpp v91, v87, v134 row_newbcast:8 row_mask:0xf bank_mask:0xf
	v_pk_fma_f32 v[138:139], v[26:27], v[90:91], v[138:139] op_sel_hi:[1,0,1] neg_lo:[0,1,0] neg_hi:[0,1,0]
	v_fma_f32 v92, -v90, s78, v92
	v_pk_fma_f32 v[140:141], v[28:29], v[90:91], v[140:141] op_sel_hi:[1,0,1] neg_lo:[0,1,0] neg_hi:[0,1,0]
	v_add_f32_dpp v93, v87, v135 row_newbcast:12 row_mask:0xf bank_mask:0xf
	v_pk_fma_f32 v[138:139], v[34:35], v[92:93], v[138:139] op_sel_hi:[1,0,1] neg_lo:[0,1,0] neg_hi:[0,1,0]
	v_pk_fma_f32 v[140:141], v[36:37], v[92:93], v[140:141] op_sel_hi:[1,0,1] neg_lo:[0,1,0] neg_hi:[0,1,0]
	s_waitcnt lgkmcnt(0)
	s_load_dwordx8 s[4:11], s[96:97], 0x1e0
	v_pk_mul_f32 v[82:83], v[138:139], v[6:7]
	v_fma_f32 v91, -v90, s76, v91
	v_pk_mul_f32 v[84:85], v[138:139], v[10:11]
	v_fma_f32 v93, -v90, s82, v93
	v_pk_mul_f32 v[86:87], v[138:139], v[14:15]
	v_fma_f32 v93, -v92, s80, v93
	v_pk_mul_f32 v[88:89], v[138:139], v[18:19]
	ds_write2_b32 v166, v91, v93 offset0:128 offset1:144
	v_pk_fma_f32 v[82:83], v[140:141], v[8:9], v[82:83]
	ds_read_b128 v[22:25], v0 offset:48128
	v_pk_fma_f32 v[84:85], v[140:141], v[12:13], v[84:85]
	ds_read_b128 v[26:29], v0 offset:48384
	v_pk_fma_f32 v[86:87], v[140:141], v[16:17], v[86:87]
	ds_read_b128 v[30:33], v0 offset:48640
	v_pk_fma_f32 v[88:89], v[140:141], v[20:21], v[88:89]
	ds_read_b128 v[34:37], v0 offset:48896
	v_pk_mul_f32 v[138:139], v[138:139], v[42:43]
	ds_read_b128 v[38:41], v0 offset:49152
	v_pk_mul_f32 v[140:141], v[140:141], v[44:45]
	ds_read2st64_b32 v[62:63], v158 offset0:193 offset1:194
	v_add_f32_e32 v82, v82, v83
	v_add_f32_e32 v84, v84, v85
	v_add_f32_e32 v86, v86, v87
	v_add_f32_e32 v88, v88, v89
	ds_read_b128 v[6:9], v0 offset:47104
	ds_read_b128 v[10:13], v0 offset:47360
	ds_read_b128 v[14:17], v0 offset:47616
	ds_read_b128 v[18:21], v0 offset:47872
	v_add_f32_dpp v83, v82, v82 row_mirror row_mask:0xf bank_mask:0xf
	v_add_f32_dpp v83, v84, v84 row_mirror row_mask:0xf bank_mask:0xc
	v_add_f32_dpp v85, v86, v86 row_mirror row_mask:0xf bank_mask:0xf
	v_add_f32_dpp v85, v88, v88 row_mirror row_mask:0xf bank_mask:0xc
	v_add_f32_dpp v87, v83, v83 row_half_mirror row_mask:0xf bank_mask:0xf
	v_pk_fma_f32 v[138:139], v[50:51], v[72:73], v[138:139] op_sel_hi:[1,0,1]
	v_pk_fma_f32 v[140:141], v[52:53], v[72:73], v[140:141] op_sel_hi:[1,0,1]
	v_add_f32_dpp v87, v85, v85 row_half_mirror row_mask:0xf bank_mask:0xa
	v_pk_fma_f32 v[138:139], v[58:59], v[72:73], v[138:139] op_sel:[0,1,0] op_sel_hi:[1,1,1]
	v_pk_fma_f32 v[140:141], v[60:61], v[72:73], v[140:141] op_sel:[0,1,0] op_sel_hi:[1,1,1]
	v_add_f32_dpp v87, v87, v87 quad_perm:[1,0,3,2] row_mask:0xf bank_mask:0xf
	v_mul_f32_e32 v134, s89, v72
	v_mul_f32_e32 v135, s95, v72
	v_add_f32_dpp v87, v87, v87 quad_perm:[2,3,0,1] row_mask:0xf bank_mask:0xf
	v_fmac_f32_e32 v135, s93, v73
	v_mul_f32_e32 v92, s91, v72
	v_mov_b32_dpp v90, v87 row_newbcast:0 row_mask:0xf bank_mask:0xf
	v_add_f32_dpp v92, v87, v92 row_newbcast:4 row_mask:0xf bank_mask:0xf
	v_add_f32_dpp v91, v87, v134 row_newbcast:8 row_mask:0xf bank_mask:0xf
	v_pk_fma_f32 v[138:139], v[46:47], v[90:91], v[138:139] op_sel_hi:[1,0,1] neg_lo:[0,1,0] neg_hi:[0,1,0]
	v_fma_f32 v92, -v90, s90, v92
	v_pk_fma_f32 v[140:141], v[48:49], v[90:91], v[140:141] op_sel_hi:[1,0,1] neg_lo:[0,1,0] neg_hi:[0,1,0]
	v_add_f32_dpp v93, v87, v135 row_newbcast:12 row_mask:0xf bank_mask:0xf
	v_pk_fma_f32 v[138:139], v[54:55], v[92:93], v[138:139] op_sel_hi:[1,0,1] neg_lo:[0,1,0] neg_hi:[0,1,0]
	v_pk_fma_f32 v[140:141], v[56:57], v[92:93], v[140:141] op_sel_hi:[1,0,1] neg_lo:[0,1,0] neg_hi:[0,1,0]
	s_waitcnt lgkmcnt(0)
	s_add_i32 m0, s41, 1
	s_min_u32 m0, m0, 0x1ff
	s_lshl_b32 m0, m0, 9
	s_add_u32 s96, s100, m0
	s_addc_u32 s97, s101, 0
	s_load_dwordx8 s[76:83], s[96:97], 0x0
	v_pk_mul_f32 v[82:83], v[138:139], v[6:7]
	v_fma_f32 v91, -v90, s88, v91
	v_pk_mul_f32 v[84:85], v[138:139], v[10:11]
	v_fma_f32 v93, -v90, s94, v93
	v_pk_mul_f32 v[86:87], v[138:139], v[14:15]
	v_fma_f32 v93, -v92, s92, v93
	v_pk_mul_f32 v[88:89], v[138:139], v[18:19]
	ds_write2_b32 v166, v91, v93 offset0:160 offset1:176
	v_pk_fma_f32 v[82:83], v[140:141], v[8:9], v[82:83]
	ds_read_b128 v[42:45], v0 offset:51200
	v_pk_fma_f32 v[84:85], v[140:141], v[12:13], v[84:85]
	ds_read_b128 v[46:49], v0 offset:51456
	v_pk_fma_f32 v[86:87], v[140:141], v[16:17], v[86:87]
	ds_read_b128 v[50:53], v0 offset:51712
	v_pk_fma_f32 v[88:89], v[140:141], v[20:21], v[88:89]
	ds_read_b128 v[54:57], v0 offset:51968
	v_pk_mul_f32 v[138:139], v[138:139], v[22:23]
	ds_read_b128 v[58:61], v0 offset:52224
	v_pk_mul_f32 v[140:141], v[140:141], v[24:25]
	ds_read2st64_b32 v[72:73], v158 offset0:205 offset1:206
	v_add_f32_e32 v82, v82, v83
	v_add_f32_e32 v84, v84, v85
	v_add_f32_e32 v86, v86, v87
	v_add_f32_e32 v88, v88, v89
	ds_read_b128 v[6:9], v0 offset:50176
	ds_read_b128 v[10:13], v0 offset:50432
	ds_read_b128 v[14:17], v0 offset:50688
	ds_read_b128 v[18:21], v0 offset:50944
	v_add_f32_dpp v83, v82, v82 row_mirror row_mask:0xf bank_mask:0xf
	v_add_f32_dpp v83, v84, v84 row_mirror row_mask:0xf bank_mask:0xc
	v_add_f32_dpp v85, v86, v86 row_mirror row_mask:0xf bank_mask:0xf
	v_add_f32_dpp v85, v88, v88 row_mirror row_mask:0xf bank_mask:0xc
	v_add_f32_dpp v87, v83, v83 row_half_mirror row_mask:0xf bank_mask:0xf
	v_pk_fma_f32 v[138:139], v[30:31], v[62:63], v[138:139] op_sel_hi:[1,0,1]
	v_pk_fma_f32 v[140:141], v[32:33], v[62:63], v[140:141] op_sel_hi:[1,0,1]
	v_add_f32_dpp v87, v85, v85 row_half_mirror row_mask:0xf bank_mask:0xa
	v_pk_fma_f32 v[138:139], v[38:39], v[62:63], v[138:139] op_sel:[0,1,0] op_sel_hi:[1,1,1]
	v_pk_fma_f32 v[140:141], v[40:41], v[62:63], v[140:141] op_sel:[0,1,0] op_sel_hi:[1,1,1]
	v_add_f32_dpp v87, v87, v87 quad_perm:[1,0,3,2] row_mask:0xf bank_mask:0xf
	v_mul_f32_e32 v134, s29, v62
	v_mul_f32_e32 v135, s35, v62
	v_add_f32_dpp v87, v87, v87 quad_perm:[2,3,0,1] row_mask:0xf bank_mask:0xf
	v_fmac_f32_e32 v135, s33, v63
	v_mul_f32_e32 v92, s31, v62
	v_mov_b32_dpp v90, v87 row_newbcast:0 row_mask:0xf bank_mask:0xf
	v_add_f32_dpp v92, v87, v92 row_newbcast:4 row_mask:0xf bank_mask:0xf
	v_add_f32_dpp v91, v87, v134 row_newbcast:8 row_mask:0xf bank_mask:0xf
	v_pk_fma_f32 v[138:139], v[26:27], v[90:91], v[138:139] op_sel_hi:[1,0,1] neg_lo:[0,1,0] neg_hi:[0,1,0]
	v_fma_f32 v92, -v90, s30, v92
	v_pk_fma_f32 v[140:141], v[28:29], v[90:91], v[140:141] op_sel_hi:[1,0,1] neg_lo:[0,1,0] neg_hi:[0,1,0]
	v_add_f32_dpp v93, v87, v135 row_newbcast:12 row_mask:0xf bank_mask:0xf
	v_pk_fma_f32 v[138:139], v[34:35], v[92:93], v[138:139] op_sel_hi:[1,0,1] neg_lo:[0,1,0] neg_hi:[0,1,0]
	v_pk_fma_f32 v[140:141], v[36:37], v[92:93], v[140:141] op_sel_hi:[1,0,1] neg_lo:[0,1,0] neg_hi:[0,1,0]
	s_waitcnt lgkmcnt(0)
	s_load_dwordx8 s[88:95], s[96:97], 0x20
	v_pk_mul_f32 v[82:83], v[138:139], v[6:7]
	v_fma_f32 v91, -v90, s28, v91
	v_pk_mul_f32 v[84:85], v[138:139], v[10:11]
	v_fma_f32 v93, -v90, s34, v93
	v_pk_mul_f32 v[86:87], v[138:139], v[14:15]
	v_fma_f32 v93, -v92, s32, v93
	v_pk_mul_f32 v[88:89], v[138:139], v[18:19]
	ds_write2_b32 v166, v91, v93 offset0:192 offset1:208
	v_pk_fma_f32 v[82:83], v[140:141], v[8:9], v[82:83]
	v_pk_fma_f32 v[84:85], v[140:141], v[12:13], v[84:85]
	v_pk_fma_f32 v[86:87], v[140:141], v[16:17], v[86:87]
	v_pk_fma_f32 v[88:89], v[140:141], v[20:21], v[88:89]
	v_pk_mul_f32 v[138:139], v[138:139], v[42:43]
	v_pk_mul_f32 v[140:141], v[140:141], v[44:45]
	v_add_f32_e32 v82, v82, v83
	v_add_f32_e32 v84, v84, v85
	v_add_f32_e32 v86, v86, v87
	v_add_f32_e32 v88, v88, v89
	v_add_f32_dpp v83, v82, v82 row_mirror row_mask:0xf bank_mask:0xf
	v_add_f32_dpp v83, v84, v84 row_mirror row_mask:0xf bank_mask:0xc
	v_add_f32_dpp v85, v86, v86 row_mirror row_mask:0xf bank_mask:0xf
	v_add_f32_dpp v85, v88, v88 row_mirror row_mask:0xf bank_mask:0xc
	v_add_f32_dpp v87, v83, v83 row_half_mirror row_mask:0xf bank_mask:0xf
	v_pk_fma_f32 v[138:139], v[50:51], v[72:73], v[138:139] op_sel_hi:[1,0,1]
	v_pk_fma_f32 v[140:141], v[52:53], v[72:73], v[140:141] op_sel_hi:[1,0,1]
	v_add_f32_dpp v87, v85, v85 row_half_mirror row_mask:0xf bank_mask:0xa
	v_pk_fma_f32 v[138:139], v[58:59], v[72:73], v[138:139] op_sel:[0,1,0] op_sel_hi:[1,1,1]
	v_pk_fma_f32 v[140:141], v[60:61], v[72:73], v[140:141] op_sel:[0,1,0] op_sel_hi:[1,1,1]
	v_add_f32_dpp v87, v87, v87 quad_perm:[1,0,3,2] row_mask:0xf bank_mask:0xf
	v_mul_f32_e32 v134, s5, v72
	v_mul_f32_e32 v135, s11, v72
	v_add_f32_dpp v87, v87, v87 quad_perm:[2,3,0,1] row_mask:0xf bank_mask:0xf
	v_fmac_f32_e32 v135, s9, v73
	v_mul_f32_e32 v92, s7, v72
	v_mov_b32_dpp v90, v87 row_newbcast:0 row_mask:0xf bank_mask:0xf
	v_add_f32_dpp v92, v87, v92 row_newbcast:4 row_mask:0xf bank_mask:0xf
	v_add_f32_dpp v91, v87, v134 row_newbcast:8 row_mask:0xf bank_mask:0xf
	v_pk_fma_f32 v[138:139], v[46:47], v[90:91], v[138:139] op_sel_hi:[1,0,1] neg_lo:[0,1,0] neg_hi:[0,1,0]
	v_fma_f32 v92, -v90, s6, v92
	v_pk_fma_f32 v[140:141], v[48:49], v[90:91], v[140:141] op_sel_hi:[1,0,1] neg_lo:[0,1,0] neg_hi:[0,1,0]
	v_add_f32_dpp v93, v87, v135 row_newbcast:12 row_mask:0xf bank_mask:0xf
	v_pk_fma_f32 v[138:139], v[54:55], v[92:93], v[138:139] op_sel_hi:[1,0,1] neg_lo:[0,1,0] neg_hi:[0,1,0]
	v_pk_fma_f32 v[140:141], v[56:57], v[92:93], v[140:141] op_sel_hi:[1,0,1] neg_lo:[0,1,0] neg_hi:[0,1,0]
	v_fma_f32 v91, -v90, s4, v91
	v_fma_f32 v93, -v90, s10, v93
	v_fma_f32 v93, -v92, s8, v93
	ds_write2_b32 v166, v91, v93 offset0:224 offset1:240
